# adds: s_setprio flips also removed from the input-projection, pool and FFN-down GEMM K-loops; 12 dead address SALU removed from the scan producer step
# speedup vs baseline: 1.0076x; 1.0010x over previous
; #define PG8_STAGE(bufoff, gbase, voff) do { _Pragma("unroll") for (int _i = 0; _i < 2; ++_i) \
;         __builtin_amdgcn_global_load_lds((const unsigned*)((const char*)(gbase) + (voff)[_i]), (LAS unsigned*)(lds + (bufoff) + ldsw + _i * 8192), 16, 0, 0); } while (0)
; #define PG8_LDA(dst, b, h) do { _Pragma("unroll") for (int m = 0; m < 4; ++m) _Pragma("unroll") for (int k = 0; k < 2; ++k) dst[m][k] = *(const LAS bf16x8*)(lds + PG8_SA(b, h) + aoff + m * 2048 + k * 1024); } while (0)
; #define PG8_LDB(dst, b, h) do { _Pragma("unroll") for (int n = 0; n < 2; ++n) _Pragma("unroll") for (int k = 0; k < 2; ++k) dst[n][k] = *(const LAS bf16x8*)(lds + PG8_SB(b, h) + boff + n * 2048 + k * 1024); } while (0)
; #define PG8_MMA(ai, bj, At, Bt) do { __builtin_amdgcn_s_setprio(1); _Pragma("unroll") for (int m = 0; m < 4; ++m) _Pragma("unroll") for (int n = 0; n < 2; ++n) _Pragma("unroll") for (int k = 0; k < 2; ++k) \
;         acc[ai][bj][m][n] = __builtin_amdgcn_mfma_f32_16x16x32_bf16(Bt[n][k], At[m][k], acc[ai][bj][m][n], 0, 0, 0); __builtin_amdgcn_s_setprio(0); } while (0)
; #define PG8_WAIT_V(n) asm volatile("s_waitcnt vmcnt(" #n ")" ::: "memory")
; #define PG8_WAIT_L(n) asm volatile("s_waitcnt lgkmcnt(" #n ")" ::: "memory")
; #define PG8_BAR __builtin_amdgcn_s_barrier()
; #define PG8_SCHED __builtin_amdgcn_sched_barrier(0)
; template <class Epi, class Sched>
; __device__ __forceinline__ void gemm_phase(LAS unsigned char* lds, const Gemm g, const Sched& S, const Epi& E) {
;     ...
;             PG8_LDB(B0, 0, 0); PG8_LDB(B1, 0, 1); PG8_SCHED; PG8_LDA(At, 0, 0); PG8_STAGE(PG8_SA(1, 1), a1 + hstepA, voffA);
;             PG8_WAIT_V(8); PG8_WAIT_L(0); PG8_BAR; PG8_MMA(0, 0, At, B0); PG8_MMA(0, 1, At, B1); PG8_BAR; PG8_SCHED;
;             PG8_LDA(At, 0, 1); PG8_STAGE(PG8_SB(0, 0), b2, voffB); PG8_STAGE(PG8_SB(0, 1), b2 + hstepB, voffB); PG8_STAGE(PG8_SA(0, 0), a2, voffA);
;             PG8_WAIT_V(8); PG8_WAIT_L(0); PG8_BAR; PG8_MMA(1, 0, At, B0); PG8_MMA(1, 1, At, B1); PG8_BAR; PG8_SCHED;
.LBB0_96:
	s_add_u32 s0, s42, 0xfffc0080
	s_addc_u32 s6, s43, -1
	s_add_i32 s26, 0, 0x10000
	s_cmp_eq_u32 s69, 12
	s_cselect_b32 s15, s13, s6
	s_cselect_b32 s14, s57, s0
	v_add_u32_e32 v152, s26, v156
	s_cselect_b32 s7, s45, s53
	s_cselect_b32 s6, s68, s52
	s_add_i32 s0, 0, 0x14000
	ds_read_b128 v[144:147], v152
	ds_read_b128 v[148:151], v152 offset:1024
	ds_read_b128 v[164:167], v152 offset:2048
	ds_read_b128 v[168:171], v152 offset:3072
	v_add_u32_e32 v152, s0, v156
	ds_read_b128 v[172:175], v152
	ds_read_b128 v[190:193], v152 offset:1024
	ds_read_b128 v[196:199], v152 offset:2048
	ds_read_b128 v[200:203], v152 offset:3072
	v_lshl_add_u64 v[152:153], s[42:43], 0, v[140:141]
	s_add_i32 m0, s21, 0xc000
	ds_read_b128 v[204:207], v162
	ds_read_b128 v[208:211], v162 offset:1024
	ds_read_b128 v[212:215], v162 offset:2048
	ds_read_b128 v[216:219], v162 offset:3072
	ds_read_b128 v[220:223], v162 offset:4096
	ds_read_b128 v[224:227], v162 offset:5120
	ds_read_b128 v[228:231], v162 offset:6144
	ds_read_b128 v[232:235], v162 offset:7168
	global_load_lds_dwordx4 v[152:153], off
	v_lshl_add_u64 v[152:153], s[42:43], 0, v[142:143]
	s_add_i32 m0, s21, 0xe000
	s_nop 0
	global_load_lds_dwordx4 v[152:153], off
	s_waitcnt vmcnt(8)
	s_waitcnt lgkmcnt(0)
	s_barrier
	s_waitcnt lgkmcnt(0)
	v_mfma_f32_16x16x32_bf16 v[128:131], v[144:147], v[204:207], v[128:131]
	v_mfma_f32_16x16x32_bf16 v[124:127], v[164:167], v[204:207], v[124:127]
	v_mfma_f32_16x16x32_bf16 v[120:123], v[144:147], v[212:215], v[120:123]
	v_mfma_f32_16x16x32_bf16 v[108:111], v[164:167], v[212:215], v[108:111]
	v_mfma_f32_16x16x32_bf16 v[104:107], v[144:147], v[220:223], v[104:107]
	v_mfma_f32_16x16x32_bf16 v[92:95], v[164:167], v[220:223], v[92:95]
	v_mfma_f32_16x16x32_bf16 v[88:91], v[144:147], v[228:231], v[88:91]
	v_mfma_f32_16x16x32_bf16 v[76:79], v[164:167], v[228:231], v[76:79]
	v_mfma_f32_16x16x32_bf16 v[128:131], v[148:151], v[208:211], v[128:131]
	v_mfma_f32_16x16x32_bf16 v[124:127], v[168:171], v[208:211], v[124:127]
	v_mfma_f32_16x16x32_bf16 v[120:123], v[148:151], v[216:219], v[120:123]
	v_mfma_f32_16x16x32_bf16 v[108:111], v[168:171], v[216:219], v[108:111]
	v_mfma_f32_16x16x32_bf16 v[104:107], v[148:151], v[224:227], v[104:107]
	v_mfma_f32_16x16x32_bf16 v[92:95], v[168:171], v[224:227], v[92:95]
	v_mfma_f32_16x16x32_bf16 v[88:91], v[148:151], v[232:235], v[88:91]
	v_mfma_f32_16x16x32_bf16 v[76:79], v[168:171], v[232:235], v[76:79]
	v_mfma_f32_16x16x32_bf16 v[116:119], v[172:175], v[204:207], v[116:119]
	v_mfma_f32_16x16x32_bf16 v[112:115], v[196:199], v[204:207], v[112:115]
	v_mfma_f32_16x16x32_bf16 v[100:103], v[172:175], v[212:215], v[100:103]
	v_mfma_f32_16x16x32_bf16 v[96:99], v[196:199], v[212:215], v[96:99]
	v_mfma_f32_16x16x32_bf16 v[84:87], v[172:175], v[220:223], v[84:87]
	v_mfma_f32_16x16x32_bf16 v[80:83], v[196:199], v[220:223], v[80:83]
	v_mfma_f32_16x16x32_bf16 v[72:75], v[172:175], v[228:231], v[72:75]
	v_mfma_f32_16x16x32_bf16 v[68:71], v[196:199], v[228:231], v[68:71]
	v_mfma_f32_16x16x32_bf16 v[116:119], v[190:193], v[208:211], v[116:119]
	v_mfma_f32_16x16x32_bf16 v[112:115], v[200:203], v[208:211], v[112:115]
	v_mfma_f32_16x16x32_bf16 v[100:103], v[190:193], v[216:219], v[100:103]
	v_mfma_f32_16x16x32_bf16 v[96:99], v[200:203], v[216:219], v[96:99]
	v_mfma_f32_16x16x32_bf16 v[84:87], v[190:193], v[224:227], v[84:87]
	v_mfma_f32_16x16x32_bf16 v[80:83], v[200:203], v[224:227], v[80:83]
	v_mfma_f32_16x16x32_bf16 v[72:75], v[190:193], v[232:235], v[72:75]
	v_mfma_f32_16x16x32_bf16 v[68:71], v[200:203], v[232:235], v[68:71]
	s_barrier
	s_add_i32 s26, s26, s20
	v_lshl_add_u64 v[152:153], s[6:7], 0, v[160:161]
	s_mov_b32 m0, s26
	ds_read_b128 v[204:207], v162 offset:16384
	ds_read_b128 v[208:211], v162 offset:17408
	ds_read_b128 v[212:215], v162 offset:18432
	ds_read_b128 v[216:219], v162 offset:19456
	ds_read_b128 v[220:223], v162 offset:20480
	ds_read_b128 v[224:227], v162 offset:21504
	ds_read_b128 v[228:231], v162 offset:22528
	ds_read_b128 v[232:235], v162 offset:23552
	global_load_lds_dwordx4 v[152:153], off
	s_add_i32 m0, s26, 0x2000
	s_add_u32 s78, s6, 0x40000
	v_lshl_add_u64 v[176:177], s[6:7], 0, v[136:137]
	s_addc_u32 s79, s7, 0
	s_add_i32 s0, s0, s20
	global_load_lds_dwordx4 v[176:177], off
	v_lshl_add_u64 v[236:237], s[78:79], 0, v[160:161]
	s_mov_b32 m0, s0
	v_lshl_add_u64 v[238:239], s[14:15], 0, v[134:135]
	global_load_lds_dwordx4 v[236:237], off
	v_lshl_add_u64 v[236:237], s[78:79], 0, v[136:137]
	s_add_i32 m0, s0, 0x2000
	s_nop 0
	global_load_lds_dwordx4 v[236:237], off
	v_lshl_add_u64 v[236:237], s[14:15], 0, v[132:133]
	s_mov_b32 m0, s21
	s_nop 0
	global_load_lds_dwordx4 v[236:237], off
	s_mov_b32 m0, s24
	s_nop 0
	global_load_lds_dwordx4 v[238:239], off
	s_waitcnt vmcnt(8)
	s_waitcnt lgkmcnt(0)
	s_barrier
; #define PG8_STAGE(bufoff, gbase, voff) do { _Pragma("unroll") for (int _i = 0; _i < 2; ++_i) \
;         __builtin_amdgcn_global_load_lds((const unsigned*)((const char*)(gbase) + (voff)[_i]), (LAS unsigned*)(lds + (bufoff) + ldsw + _i * 8192), 16, 0, 0); } while (0)
; #define PG8_LDA(dst, b, h) do { _Pragma("unroll") for (int m = 0; m < 4; ++m) _Pragma("unroll") for (int k = 0; k < 2; ++k) dst[m][k] = *(const LAS bf16x8*)(lds + PG8_SA(b, h) + aoff + m * 2048 + k * 1024); } while (0)
; #define PG8_LDB(dst, b, h) do { _Pragma("unroll") for (int n = 0; n < 2; ++n) _Pragma("unroll") for (int k = 0; k < 2; ++k) dst[n][k] = *(const LAS bf16x8*)(lds + PG8_SB(b, h) + boff + n * 2048 + k * 1024); } while (0)
; #define PG8_MMA(ai, bj, At, Bt) do { __builtin_amdgcn_s_setprio(1); _Pragma("unroll") for (int m = 0; m < 4; ++m) _Pragma("unroll") for (int n = 0; n < 2; ++n) _Pragma("unroll") for (int k = 0; k < 2; ++k) \
;         acc[ai][bj][m][n] = __builtin_amdgcn_mfma_f32_16x16x32_bf16(Bt[n][k], At[m][k], acc[ai][bj][m][n], 0, 0, 0); __builtin_amdgcn_s_setprio(0); } while (0)
; #define PG8_WAIT_V(n) asm volatile("s_waitcnt vmcnt(" #n ")" ::: "memory")
; #define PG8_WAIT_L(n) asm volatile("s_waitcnt lgkmcnt(" #n ")" ::: "memory")
; #define PG8_BAR __builtin_amdgcn_s_barrier()
; #define PG8_SCHED __builtin_amdgcn_sched_barrier(0)
; template <class Epi, class Sched>
; __device__ __forceinline__ void gemm_phase(LAS unsigned char* lds, const Gemm g, const Sched& S, const Epi& E) {
;     ...
;             PG8_WAIT_V(8); PG8_WAIT_L(0); PG8_BAR; PG8_MMA(1, 0, At, B0); PG8_MMA(1, 1, At, B1); PG8_BAR; PG8_SCHED;
;             PG8_LDB(B0, 1, 0); PG8_LDB(B1, 1, 1); PG8_SCHED; PG8_LDA(At, 1, 0); PG8_STAGE(PG8_SA(0, 1), a2 + hstepA, voffA);
;             PG8_WAIT_V(8); PG8_WAIT_L(0); PG8_BAR; PG8_MMA(0, 0, At, B0); PG8_MMA(0, 1, At, B1); PG8_BAR; PG8_SCHED;
	s_waitcnt lgkmcnt(0)
	v_mfma_f32_16x16x32_bf16 v[64:67], v[144:147], v[204:207], v[64:67]
	v_mfma_f32_16x16x32_bf16 v[60:63], v[164:167], v[204:207], v[60:63]
	v_mfma_f32_16x16x32_bf16 v[56:59], v[144:147], v[212:215], v[56:59]
	v_mfma_f32_16x16x32_bf16 v[44:47], v[164:167], v[212:215], v[44:47]
	v_mfma_f32_16x16x32_bf16 v[40:43], v[144:147], v[220:223], v[40:43]
	v_mfma_f32_16x16x32_bf16 v[28:31], v[164:167], v[220:223], v[28:31]
	v_mfma_f32_16x16x32_bf16 v[24:27], v[144:147], v[228:231], v[24:27]
	v_mfma_f32_16x16x32_bf16 v[12:15], v[164:167], v[228:231], v[12:15]
	v_mfma_f32_16x16x32_bf16 v[64:67], v[148:151], v[208:211], v[64:67]
	v_mfma_f32_16x16x32_bf16 v[60:63], v[168:171], v[208:211], v[60:63]
	v_mfma_f32_16x16x32_bf16 v[56:59], v[148:151], v[216:219], v[56:59]
	v_mfma_f32_16x16x32_bf16 v[44:47], v[168:171], v[216:219], v[44:47]
	v_mfma_f32_16x16x32_bf16 v[40:43], v[148:151], v[224:227], v[40:43]
	v_mfma_f32_16x16x32_bf16 v[28:31], v[168:171], v[224:227], v[28:31]
	v_mfma_f32_16x16x32_bf16 v[24:27], v[148:151], v[232:235], v[24:27]
	v_mfma_f32_16x16x32_bf16 v[12:15], v[168:171], v[232:235], v[12:15]
	v_mfma_f32_16x16x32_bf16 v[52:55], v[172:175], v[204:207], v[52:55]
	v_mfma_f32_16x16x32_bf16 v[48:51], v[196:199], v[204:207], v[48:51]
	v_mfma_f32_16x16x32_bf16 v[36:39], v[172:175], v[212:215], v[36:39]
	v_mfma_f32_16x16x32_bf16 v[32:35], v[196:199], v[212:215], v[32:35]
	v_mfma_f32_16x16x32_bf16 v[20:23], v[172:175], v[220:223], v[20:23]
	v_mfma_f32_16x16x32_bf16 v[16:19], v[196:199], v[220:223], v[16:19]
	v_mfma_f32_16x16x32_bf16 v[8:11], v[172:175], v[228:231], v[8:11]
	v_mfma_f32_16x16x32_bf16 v[4:7], v[196:199], v[228:231], v[4:7]
	v_mfma_f32_16x16x32_bf16 v[52:55], v[190:193], v[208:211], v[52:55]
	v_mfma_f32_16x16x32_bf16 v[48:51], v[200:203], v[208:211], v[48:51]
	v_mfma_f32_16x16x32_bf16 v[36:39], v[190:193], v[216:219], v[36:39]
	v_mfma_f32_16x16x32_bf16 v[32:35], v[200:203], v[216:219], v[32:35]
	v_mfma_f32_16x16x32_bf16 v[20:23], v[190:193], v[224:227], v[20:23]
	v_mfma_f32_16x16x32_bf16 v[16:19], v[200:203], v[224:227], v[16:19]
	v_mfma_f32_16x16x32_bf16 v[8:11], v[190:193], v[232:235], v[8:11]
	v_mfma_f32_16x16x32_bf16 v[4:7], v[200:203], v[232:235], v[4:7]
	s_barrier
	s_add_i32 s0, 0, 0x18000
	v_add_u32_e32 v163, s0, v156
	s_add_i32 s26, 0, 0x1c000
	ds_read_b128 v[144:147], v163
	ds_read_b128 v[148:151], v163 offset:1024
	ds_read_b128 v[164:167], v163 offset:2048
	ds_read_b128 v[168:171], v163 offset:3072
	v_add_u32_e32 v163, s26, v156
	ds_read_b128 v[172:175], v163
	ds_read_b128 v[190:193], v163 offset:1024
	ds_read_b128 v[196:199], v163 offset:2048
	ds_read_b128 v[200:203], v163 offset:3072
	s_add_u32 s14, s14, 0x40000
	s_addc_u32 s15, s15, 0
	s_mov_b32 m0, s25
	v_lshl_add_u64 v[240:241], s[14:15], 0, v[132:133]
	ds_read_b128 v[204:207], v162 offset:32768
	ds_read_b128 v[208:211], v162 offset:33792
	ds_read_b128 v[212:215], v162 offset:34816
	ds_read_b128 v[216:219], v162 offset:35840
	ds_read_b128 v[220:223], v162 offset:36864
	ds_read_b128 v[224:227], v162 offset:37888
	ds_read_b128 v[228:231], v162 offset:38912
	ds_read_b128 v[232:235], v162 offset:39936
	global_load_lds_dwordx4 v[240:241], off
	v_lshl_add_u64 v[240:241], s[14:15], 0, v[134:135]
	s_mov_b32 m0, s28
	s_nop 0
	global_load_lds_dwordx4 v[240:241], off
	s_waitcnt vmcnt(8)
	s_waitcnt lgkmcnt(0)
	s_barrier
	s_waitcnt lgkmcnt(0)
	v_mfma_f32_16x16x32_bf16 v[128:131], v[144:147], v[204:207], v[128:131]
	v_mfma_f32_16x16x32_bf16 v[124:127], v[164:167], v[204:207], v[124:127]
	v_mfma_f32_16x16x32_bf16 v[120:123], v[144:147], v[212:215], v[120:123]
	v_mfma_f32_16x16x32_bf16 v[108:111], v[164:167], v[212:215], v[108:111]
	v_mfma_f32_16x16x32_bf16 v[104:107], v[144:147], v[220:223], v[104:107]
	v_mfma_f32_16x16x32_bf16 v[92:95], v[164:167], v[220:223], v[92:95]
	v_mfma_f32_16x16x32_bf16 v[88:91], v[144:147], v[228:231], v[88:91]
	v_mfma_f32_16x16x32_bf16 v[76:79], v[164:167], v[228:231], v[76:79]
	v_mfma_f32_16x16x32_bf16 v[128:131], v[148:151], v[208:211], v[128:131]
	v_mfma_f32_16x16x32_bf16 v[124:127], v[168:171], v[208:211], v[124:127]
	v_mfma_f32_16x16x32_bf16 v[120:123], v[148:151], v[216:219], v[120:123]
	v_mfma_f32_16x16x32_bf16 v[108:111], v[168:171], v[216:219], v[108:111]
	v_mfma_f32_16x16x32_bf16 v[104:107], v[148:151], v[224:227], v[104:107]
	v_mfma_f32_16x16x32_bf16 v[92:95], v[168:171], v[224:227], v[92:95]
	v_mfma_f32_16x16x32_bf16 v[88:91], v[148:151], v[232:235], v[88:91]
	v_mfma_f32_16x16x32_bf16 v[76:79], v[168:171], v[232:235], v[76:79]
	v_mfma_f32_16x16x32_bf16 v[116:119], v[172:175], v[204:207], v[116:119]
	v_mfma_f32_16x16x32_bf16 v[112:115], v[196:199], v[204:207], v[112:115]
	v_mfma_f32_16x16x32_bf16 v[100:103], v[172:175], v[212:215], v[100:103]
	v_mfma_f32_16x16x32_bf16 v[96:99], v[196:199], v[212:215], v[96:99]
	v_mfma_f32_16x16x32_bf16 v[84:87], v[172:175], v[220:223], v[84:87]
	v_mfma_f32_16x16x32_bf16 v[80:83], v[196:199], v[220:223], v[80:83]
	v_mfma_f32_16x16x32_bf16 v[72:75], v[172:175], v[228:231], v[72:75]
	v_mfma_f32_16x16x32_bf16 v[68:71], v[196:199], v[228:231], v[68:71]
	v_mfma_f32_16x16x32_bf16 v[116:119], v[190:193], v[208:211], v[116:119]
	v_mfma_f32_16x16x32_bf16 v[112:115], v[200:203], v[208:211], v[112:115]
	v_mfma_f32_16x16x32_bf16 v[100:103], v[190:193], v[216:219], v[100:103]
	v_mfma_f32_16x16x32_bf16 v[96:99], v[200:203], v[216:219], v[96:99]
	v_mfma_f32_16x16x32_bf16 v[84:87], v[190:193], v[224:227], v[84:87]
	v_mfma_f32_16x16x32_bf16 v[80:83], v[200:203], v[224:227], v[80:83]
	v_mfma_f32_16x16x32_bf16 v[72:75], v[190:193], v[232:235], v[72:75]
	v_mfma_f32_16x16x32_bf16 v[68:71], v[200:203], v[232:235], v[68:71]
	s_barrier
; #define PG8_STAGE(bufoff, gbase, voff) do { _Pragma("unroll") for (int _i = 0; _i < 2; ++_i) \
;         __builtin_amdgcn_global_load_lds((const unsigned*)((const char*)(gbase) + (voff)[_i]), (LAS unsigned*)(lds + (bufoff) + ldsw + _i * 8192), 16, 0, 0); } while (0)
; #define PG8_LDA(dst, b, h) do { _Pragma("unroll") for (int m = 0; m < 4; ++m) _Pragma("unroll") for (int k = 0; k < 2; ++k) dst[m][k] = *(const LAS bf16x8*)(lds + PG8_SA(b, h) + aoff + m * 2048 + k * 1024); } while (0)
; #define PG8_MMA(ai, bj, At, Bt) do { __builtin_amdgcn_s_setprio(1); _Pragma("unroll") for (int m = 0; m < 4; ++m) _Pragma("unroll") for (int n = 0; n < 2; ++n) _Pragma("unroll") for (int k = 0; k < 2; ++k) \
;         acc[ai][bj][m][n] = __builtin_amdgcn_mfma_f32_16x16x32_bf16(Bt[n][k], At[m][k], acc[ai][bj][m][n], 0, 0, 0); __builtin_amdgcn_s_setprio(0); } while (0)
; #define PG8_WAIT_V(n) asm volatile("s_waitcnt vmcnt(" #n ")" ::: "memory")
; #define PG8_WAIT_L(n) asm volatile("s_waitcnt lgkmcnt(" #n ")" ::: "memory")
; #define PG8_BAR __builtin_amdgcn_s_barrier()
; #define PG8_SCHED __builtin_amdgcn_sched_barrier(0)
; template <class Epi, class Sched>
; __device__ __forceinline__ void gemm_phase(LAS unsigned char* lds, const Gemm g, const Sched& S, const Epi& E) {
;     ...
;             PG8_LDA(At, 1, 1); PG8_STAGE(PG8_SB(1, 0), b3, voffB); PG8_STAGE(PG8_SB(1, 1), b3 + hstepB, voffB); PG8_STAGE(PG8_SA(1, 0), a3, voffA);
;             PG8_WAIT_V(8); PG8_WAIT_L(0); PG8_BAR; PG8_MMA(1, 0, At, B0); PG8_MMA(1, 1, At, B1); PG8_BAR; PG8_SCHED;
;         }
;         if (wr == 0) PG8_BAR;
	s_add_i32 s0, s0, s20
	v_lshl_add_u64 v[152:153], v[152:153], 0, s[30:31]
	s_mov_b32 m0, s0
	ds_read_b128 v[204:207], v162 offset:49152
	ds_read_b128 v[208:211], v162 offset:50176
	ds_read_b128 v[212:215], v162 offset:51200
	ds_read_b128 v[216:219], v162 offset:52224
	ds_read_b128 v[220:223], v162 offset:53248
	ds_read_b128 v[224:227], v162 offset:54272
	ds_read_b128 v[228:231], v162 offset:55296
	ds_read_b128 v[232:235], v162 offset:56320
	global_load_lds_dwordx4 v[152:153], off
	s_add_i32 m0, s0, 0x2000
	s_add_u32 s6, s6, 0x40080
	v_lshl_add_u64 v[152:153], v[176:177], 0, s[30:31]
	s_addc_u32 s7, s7, 0
	s_add_i32 s0, s26, s20
	global_load_lds_dwordx4 v[152:153], off
	v_lshl_add_u64 v[152:153], s[6:7], 0, v[160:161]
	s_mov_b32 m0, s0
	s_nop 0
	global_load_lds_dwordx4 v[152:153], off
	v_lshl_add_u64 v[152:153], s[6:7], 0, v[136:137]
	s_add_i32 m0, s0, 0x2000
	s_nop 0
	global_load_lds_dwordx4 v[152:153], off
	v_lshl_add_u64 v[152:153], v[236:237], 0, s[30:31]
	s_mov_b32 m0, s33
	s_nop 0
	global_load_lds_dwordx4 v[152:153], off
	v_lshl_add_u64 v[152:153], v[238:239], 0, s[30:31]
	s_mov_b32 m0, s54
	s_nop 0
	global_load_lds_dwordx4 v[152:153], off
	s_waitcnt vmcnt(8)
	s_waitcnt lgkmcnt(0)
	s_barrier
	s_waitcnt lgkmcnt(0)
	v_mfma_f32_16x16x32_bf16 v[64:67], v[144:147], v[204:207], v[64:67]
	v_mfma_f32_16x16x32_bf16 v[60:63], v[164:167], v[204:207], v[60:63]
	v_mfma_f32_16x16x32_bf16 v[56:59], v[144:147], v[212:215], v[56:59]
	v_mfma_f32_16x16x32_bf16 v[44:47], v[164:167], v[212:215], v[44:47]
	v_mfma_f32_16x16x32_bf16 v[40:43], v[144:147], v[220:223], v[40:43]
	v_mfma_f32_16x16x32_bf16 v[28:31], v[164:167], v[220:223], v[28:31]
	v_mfma_f32_16x16x32_bf16 v[24:27], v[144:147], v[228:231], v[24:27]
	v_mfma_f32_16x16x32_bf16 v[12:15], v[164:167], v[228:231], v[12:15]
	v_mfma_f32_16x16x32_bf16 v[64:67], v[148:151], v[208:211], v[64:67]
	v_mfma_f32_16x16x32_bf16 v[60:63], v[168:171], v[208:211], v[60:63]
	v_mfma_f32_16x16x32_bf16 v[56:59], v[148:151], v[216:219], v[56:59]
	v_mfma_f32_16x16x32_bf16 v[44:47], v[168:171], v[216:219], v[44:47]
	v_mfma_f32_16x16x32_bf16 v[40:43], v[148:151], v[224:227], v[40:43]
	v_mfma_f32_16x16x32_bf16 v[28:31], v[168:171], v[224:227], v[28:31]
	v_mfma_f32_16x16x32_bf16 v[24:27], v[148:151], v[232:235], v[24:27]
	v_mfma_f32_16x16x32_bf16 v[12:15], v[168:171], v[232:235], v[12:15]
	v_mfma_f32_16x16x32_bf16 v[52:55], v[172:175], v[204:207], v[52:55]
	v_mfma_f32_16x16x32_bf16 v[48:51], v[196:199], v[204:207], v[48:51]
	v_mfma_f32_16x16x32_bf16 v[36:39], v[172:175], v[212:215], v[36:39]
	v_mfma_f32_16x16x32_bf16 v[32:35], v[196:199], v[212:215], v[32:35]
	v_mfma_f32_16x16x32_bf16 v[20:23], v[172:175], v[220:223], v[20:23]
	v_mfma_f32_16x16x32_bf16 v[16:19], v[196:199], v[220:223], v[16:19]
	v_mfma_f32_16x16x32_bf16 v[8:11], v[172:175], v[228:231], v[8:11]
	v_mfma_f32_16x16x32_bf16 v[4:7], v[196:199], v[228:231], v[4:7]
	v_mfma_f32_16x16x32_bf16 v[52:55], v[190:193], v[208:211], v[52:55]
	v_mfma_f32_16x16x32_bf16 v[48:51], v[200:203], v[208:211], v[48:51]
	v_mfma_f32_16x16x32_bf16 v[36:39], v[190:193], v[216:219], v[36:39]
	v_mfma_f32_16x16x32_bf16 v[32:35], v[200:203], v[216:219], v[32:35]
	v_mfma_f32_16x16x32_bf16 v[20:23], v[190:193], v[224:227], v[20:23]
	v_mfma_f32_16x16x32_bf16 v[16:19], v[200:203], v[224:227], v[16:19]
	v_mfma_f32_16x16x32_bf16 v[8:11], v[190:193], v[232:235], v[8:11]
	v_mfma_f32_16x16x32_bf16 v[4:7], v[200:203], v[232:235], v[4:7]
	s_barrier
	s_add_i32 s69, s69, 2
	s_add_u32 s42, s42, 0x100
	s_addc_u32 s43, s43, 0
	s_add_u32 s52, s52, 0x100
	s_addc_u32 s53, s53, 0
	s_cmp_gt_u32 s69, 13
	s_cbranch_scc0 .LBB0_96
	s_and_b64 vcc, exec, s[18:19]
	s_cbranch_vccz .LBB0_99
	s_barrier

; __device__ __forceinline__ void gla_scan_phase2(LAS unsigned char* lds, const bf16_t* proj, const float* gbuf, const float* wgu  , const float* bg  ,
;                                                 bf16_t* ob0, bf16_t* ob1) {
;     ...
;                     const f32x4 ga = gna, gb = gnb;
;                     const unsigned srow = (unsigned)tok0 * (unsigned)(GINP * 2);
;                     unsigned short qv[16], kv[16];
; #pragma unroll
;                     for (int ii = 0; ii < 16; ++ii) { qv[ii] = __builtin_amdgcn_raw_buffer_load_b16(prs, qvoff, srow + (unsigned)(ii * GINP * 2), 0);
;                                                        kv[ii] = __builtin_amdgcn_raw_buffer_load_b16(prs, qvoff + 1024u, srow + (unsigned)(ii * GINP * 2), 0); }
;                     unsigned vw[16];
; #pragma unroll
;                     for (int ii = 0; ii < 16; ++ii) vw[ii] = __builtin_amdgcn_raw_buffer_load_b32(prs, vvoff, srow + (unsigned)(ii * GINP * 2), 0);
;                     { const int n1 = n + 1 < NCH ? n + 1 : n; const float* grow = gbuf + (size_t)(b * SEQ + (dir ? NCH - 1 - n1 : n1) * CH + r) * 32 + dir * 16 + 8 * hh;
;                       gna = *(const f32x4*)grow; gnb = *(const f32x4*)(grow + 4); }
;                     {
;                         u32x4 ah, al;
;                         ah.x = pk2(ga[0], ga[1]); ah.y = pk2(ga[2], ga[3]); ah.z = pk2(gb[0], gb[1]); ah.w = pk2(gb[2], gb[3]);
;                         al.x = pk2(ga[0] - bflo(ah.x), ga[1] - bfhi(ah.x)); al.y = pk2(ga[2] - bflo(ah.y), ga[3] - bfhi(ah.y));
;                         al.z = pk2(gb[0] - bflo(ah.z), gb[1] - bfhi(ah.z)); al.w = pk2(gb[2] - bflo(ah.w), gb[3] - bfhi(ah.w));
;                         const bf16x8 gah = __builtin_bit_cast(bf16x8, ah), gal = __builtin_bit_cast(bf16x8, al);
;                         f32x16 zacc;
; #pragma unroll
;                         for (int i = 0; i < 16; ++i) zacc[i] = zbias;
;                         zacc = MFMA32(gah, wbh, zacc); zacc = MFMA32(gal, wbh, zacc); zacc = MFMA32(gah, wbl, zacc);
; #pragma unroll
;                         for (int i = 0; i < 16; ++i) *(LAS float*)(lds + G2_Z + (((i & 3) + 8 * (i >> 2) + 4 * hh) * 128 + 32 * zd + r) * 4) = zacc[i];
;                     }
;                     G2_BAR();
;                     float cs[16];
; #pragma unroll
;                     for (int ii = 0; ii < 16; ++ii) {
.LBB0_220:
	s_waitcnt vmcnt(4)
	v_cvt_pk_bf16_f32 v102, v44, v45
	v_lshlrev_b32_e32 v16, 16, v102
	v_and_b32_e32 v17, 0xffff0000, v102
	v_cvt_pk_bf16_f32 v103, v46, v47
	v_cvt_pk_bf16_f32 v104, v40, v41
	v_cvt_pk_bf16_f32 v105, v42, v43
	v_pk_add_f32 v[16:17], v[44:45], v[16:17] neg_lo:[0,1] neg_hi:[0,1]
	s_and_b64 s[6:7], s[48:49], exec
	v_cvt_pk_bf16_f32 v44, v16, v17
	v_lshlrev_b32_e32 v16, 16, v103
	v_and_b32_e32 v17, 0xffff0000, v103
	v_pk_add_f32 v[16:17], v[46:47], v[16:17] neg_lo:[0,1] neg_hi:[0,1]
	s_cselect_b32 s0, s20, s8
	v_cvt_pk_bf16_f32 v45, v16, v17
	v_lshlrev_b32_e32 v16, 16, v104
	v_and_b32_e32 v17, 0xffff0000, v104
	v_pk_add_f32 v[16:17], v[40:41], v[16:17] neg_lo:[0,1] neg_hi:[0,1]
	v_lshlrev_b32_e32 v40, 16, v105
	v_cvt_pk_bf16_f32 v46, v16, v17
	v_mfma_f32_32x32x16_bf16 v[16:31], v[102:105], v[32:35], v[0:15]
	v_and_b32_e32 v41, 0xffff0000, v105
	v_add_f32_e64 v40, v42, -v40
	v_add_f32_e64 v41, v43, -v41
	s_lshl_b32 s0, s0, 5
	v_cvt_pk_bf16_f32 v47, v40, v41
	s_add_i32 s0, s0, s9
	s_mulk_i32 s0, 0x1a00
	s_or_b32 s6, s0, 0x1a00
	v_mfma_f32_32x32x16_bf16 v[16:31], v[44:47], v[32:35], v[16:31]
	s_or_b32 s7, s0, 0x3400
	s_add_i32 s15, s0, 0x4e00
	s_cmp_lt_u32 s20, 63
	buffer_load_dwordx4 v[54:57], v176, s[64:67], s0 offen
	buffer_load_dwordx4 v[58:61], v176, s[64:67], s6 offen
	buffer_load_dwordx4 v[62:65], v176, s[64:67], s7 offen
	buffer_load_dwordx4 v[66:69], v176, s[64:67], s15 offen
	s_cselect_b64 s[6:7], -1, 0
	s_cmp_lg_u64 s[6:7], 0
	s_addc_u32 s0, s20, 0
	s_cmp_lg_u64 s[6:7], 0
	s_subb_u32 s6, 0, 0
	v_mfma_f32_32x32x16_bf16 v[16:31], v[102:105], v[36:39], v[16:31]
	s_add_i32 s15, s8, s6
	s_and_b64 s[6:7], s[48:49], exec
	s_cselect_b32 s0, s0, s15
	v_lshl_add_u32 v40, s0, 5, v52
	v_ashrrev_i32_e32 v41, 31, v40
	v_lshlrev_b64 v[40:41], 7, v[40:41]
	v_lshl_add_u64 v[44:45], v[48:49], 0, v[40:41]
	global_load_dwordx4 v[40:43], v[44:45], off offset:16
	s_nop 0
	global_load_dwordx4 v[44:47], v[44:45], off
	s_nop 1
	ds_write_b32 v214, v16
	ds_write_b32 v215, v17
	ds_write_b32 v216, v18
	ds_write_b32 v217, v19
	ds_write_b32 v218, v20
	ds_write_b32 v219, v21
	ds_write_b32 v220, v22
	ds_write_b32 v221, v23
	ds_write_b32 v222, v24
	ds_write_b32 v223, v25
	ds_write_b32 v224, v26
	ds_write_b32 v225, v27
	ds_write_b32 v226, v28
	ds_write_b32 v227, v29
	ds_write_b32 v228, v30
	ds_write_b32 v229, v31
	s_waitcnt lgkmcnt(0)
	s_barrier
	ds_read2st64_b32 v[118:119], v230 offset1:2
	ds_read2st64_b32 v[120:121], v230 offset0:4 offset1:6
	ds_read2st64_b32 v[122:123], v230 offset0:8 offset1:10
	ds_read2st64_b32 v[124:125], v230 offset0:12 offset1:14
	ds_read2st64_b32 v[126:127], v230 offset0:16 offset1:18
	ds_read2st64_b32 v[128:129], v230 offset0:20 offset1:22
	ds_read2st64_b32 v[130:131], v230 offset0:24 offset1:26
	ds_read2st64_b32 v[132:133], v230 offset0:28 offset1:30
	s_andn2_b64 vcc, exec, s[68:69]
	s_mov_b64 s[6:7], -1
	s_waitcnt lgkmcnt(4)
	v_mul_f32_e64 v134, |v118|, s1
	v_mul_f32_e64 v135, |v119|, s1
	v_mul_f32_e64 v136, |v120|, s1
	v_mul_f32_e64 v137, |v121|, s1
	v_mul_f32_e64 v138, |v122|, s1
	v_mul_f32_e64 v139, |v123|, s1
	v_mul_f32_e64 v140, |v124|, s1
	v_mul_f32_e64 v141, |v125|, s1
	s_waitcnt lgkmcnt(0)
	v_mul_f32_e64 v142, |v126|, s1
	v_mul_f32_e64 v143, |v127|, s1
	v_mul_f32_e64 v144, |v128|, s1
	v_mul_f32_e64 v145, |v129|, s1
	v_mul_f32_e64 v146, |v130|, s1
	v_mul_f32_e64 v147, |v131|, s1
	v_mul_f32_e64 v148, |v132|, s1
	v_mul_f32_e64 v149, |v133|, s1
	v_exp_f32_e32 v134, v134
	v_exp_f32_e32 v135, v135
	v_exp_f32_e32 v136, v136
	v_exp_f32_e32 v137, v137
	v_exp_f32_e32 v138, v138
	v_exp_f32_e32 v139, v139
	v_exp_f32_e32 v140, v140
	v_exp_f32_e32 v141, v141
	v_exp_f32_e32 v142, v142
	v_exp_f32_e32 v143, v143
	v_exp_f32_e32 v144, v144
	v_exp_f32_e32 v145, v145
	v_exp_f32_e32 v146, v146
	v_exp_f32_e32 v147, v147
	v_exp_f32_e32 v148, v148
	v_exp_f32_e32 v149, v149
	v_min_f32_e32 v118, 0, v118
	v_min_f32_e32 v119, 0, v119
	v_min_f32_e32 v120, 0, v120
	v_min_f32_e32 v121, 0, v121
	v_min_f32_e32 v122, 0, v122
	v_min_f32_e32 v123, 0, v123
	v_min_f32_e32 v124, 0, v124
	v_min_f32_e32 v125, 0, v125
	v_min_f32_e32 v126, 0, v126
	v_min_f32_e32 v127, 0, v127
	v_min_f32_e32 v128, 0, v128
	v_min_f32_e32 v129, 0, v129
	v_min_f32_e32 v130, 0, v130
	v_min_f32_e32 v131, 0, v131
	v_min_f32_e32 v132, 0, v132
	v_min_f32_e32 v133, 0, v133
	v_add_f32_e32 v134, 1.0, v134
	v_add_f32_e32 v135, 1.0, v135
	v_add_f32_e32 v136, 1.0, v136
	v_add_f32_e32 v137, 1.0, v137
	v_add_f32_e32 v138, 1.0, v138
	v_add_f32_e32 v139, 1.0, v139
	v_add_f32_e32 v140, 1.0, v140
	v_add_f32_e32 v141, 1.0, v141
	v_add_f32_e32 v142, 1.0, v142
	v_add_f32_e32 v143, 1.0, v143
	v_add_f32_e32 v144, 1.0, v144
	v_add_f32_e32 v145, 1.0, v145
	v_add_f32_e32 v146, 1.0, v146
	v_add_f32_e32 v147, 1.0, v147
	v_add_f32_e32 v148, 1.0, v148
	v_add_f32_e32 v149, 1.0, v149
	v_log_f32_e32 v134, v134
	v_log_f32_e32 v135, v135
	v_log_f32_e32 v136, v136
	v_log_f32_e32 v137, v137
	v_log_f32_e32 v138, v138
	v_log_f32_e32 v139, v139
	v_log_f32_e32 v140, v140
	v_log_f32_e32 v141, v141
	v_log_f32_e32 v142, v142
	v_log_f32_e32 v143, v143
	v_log_f32_e32 v144, v144
	v_log_f32_e32 v145, v145
	v_log_f32_e32 v146, v146
	v_log_f32_e32 v147, v147
	v_log_f32_e32 v148, v148
	v_log_f32_e32 v149, v149
	v_mul_f32_e32 v134, 0x3d800000, v134
	v_mul_f32_e32 v135, 0x3d800000, v135
	v_mul_f32_e32 v136, 0x3d800000, v136
	v_mul_f32_e32 v137, 0x3d800000, v137
	v_mul_f32_e32 v138, 0x3d800000, v138
	v_mul_f32_e32 v139, 0x3d800000, v139
	v_mul_f32_e32 v140, 0x3d800000, v140
	v_mul_f32_e32 v141, 0x3d800000, v141
	v_mul_f32_e32 v142, 0x3d800000, v142
	v_mul_f32_e32 v143, 0x3d800000, v143
	v_mul_f32_e32 v144, 0x3d800000, v144
	v_mul_f32_e32 v145, 0x3d800000, v145
	v_mul_f32_e32 v146, 0x3d800000, v146
	v_mul_f32_e32 v147, 0x3d800000, v147
	v_mul_f32_e32 v148, 0x3d800000, v148
	v_mul_f32_e32 v149, 0x3d800000, v149
	v_fma_f32 v16, v118, s10, -v134
	v_fma_f32 v25, v119, s10, -v135
	v_fma_f32 v26, v120, s10, -v136
	v_fma_f32 v29, v121, s10, -v137
	v_fma_f32 v30, v122, s10, -v138
	v_fma_f32 v102, v123, s10, -v139
	v_fma_f32 v104, v124, s10, -v140
	v_fma_f32 v105, v125, s10, -v141
	v_fma_f32 v108, v126, s10, -v142
	v_fma_f32 v109, v127, s10, -v143
	v_fma_f32 v111, v128, s10, -v144
	v_fma_f32 v112, v129, s10, -v145
	v_fma_f32 v113, v130, s10, -v146
	v_fma_f32 v114, v131, s10, -v147
	v_fma_f32 v116, v132, s10, -v148
	v_fma_f32 v17, v133, s10, -v149
	s_cbranch_vccnz .LBB0_222
	v_add_f32_e32 v18, v116, v17
	v_add_f32_e32 v19, v114, v18
	v_add_f32_e32 v20, v113, v19
	v_add_f32_e32 v21, v112, v20
	v_add_f32_e32 v22, v111, v21
	v_add_f32_e32 v23, v109, v22
	v_add_f32_e32 v24, v108, v23
	v_add_f32_e32 v27, v105, v24
	v_add_f32_e32 v28, v104, v27
	v_add_f32_e32 v31, v102, v28
	v_add_f32_e32 v103, v30, v31
	v_add_f32_e32 v106, v29, v103
	v_add_f32_e32 v107, v26, v106
	v_add_f32_e32 v110, v25, v107
	v_add_f32_e32 v115, v16, v110
	s_mov_b64 s[6:7], 0

; #define PG8_STAGE(bufoff, gbase, voff) do { _Pragma("unroll") for (int _i = 0; _i < 2; ++_i) \
;         __builtin_amdgcn_global_load_lds((const unsigned*)((const char*)(gbase) + (voff)[_i]), (LAS unsigned*)(lds + (bufoff) + ldsw + _i * 8192), 16, 0, 0); } while (0)
; #define PG8_LDA(dst, b, h) do { _Pragma("unroll") for (int m = 0; m < 4; ++m) _Pragma("unroll") for (int k = 0; k < 2; ++k) dst[m][k] = *(const LAS bf16x8*)(lds + PG8_SA(b, h) + aoff + m * 2048 + k * 1024); } while (0)
; #define PG8_LDB(dst, b, h) do { _Pragma("unroll") for (int n = 0; n < 2; ++n) _Pragma("unroll") for (int k = 0; k < 2; ++k) dst[n][k] = *(const LAS bf16x8*)(lds + PG8_SB(b, h) + boff + n * 2048 + k * 1024); } while (0)
; #define PG8_MMA(ai, bj, At, Bt) do { __builtin_amdgcn_s_setprio(1); _Pragma("unroll") for (int m = 0; m < 4; ++m) _Pragma("unroll") for (int n = 0; n < 2; ++n) _Pragma("unroll") for (int k = 0; k < 2; ++k) \
;         acc[ai][bj][m][n] = __builtin_amdgcn_mfma_f32_16x16x32_bf16(Bt[n][k], At[m][k], acc[ai][bj][m][n], 0, 0, 0); __builtin_amdgcn_s_setprio(0); } while (0)
; #define PG8_WAIT_V(n) asm volatile("s_waitcnt vmcnt(" #n ")" ::: "memory")
; #define PG8_WAIT_L(n) asm volatile("s_waitcnt lgkmcnt(" #n ")" ::: "memory")
; #define PG8_BAR __builtin_amdgcn_s_barrier()
; #define PG8_SCHED __builtin_amdgcn_sched_barrier(0)
; template <class Epi, class Sched>
; __device__ __forceinline__ void gemm_phase(LAS unsigned char* lds, const Gemm g, const Sched& S, const Epi& E) {
;     ...
;             PG8_LDB(B0, 0, 0); PG8_LDB(B1, 0, 1); PG8_SCHED; PG8_LDA(At, 0, 0); PG8_STAGE(PG8_SA(1, 1), a1 + hstepA, voffA);
;             PG8_WAIT_V(8); PG8_WAIT_L(0); PG8_BAR; PG8_MMA(0, 0, At, B0); PG8_MMA(0, 1, At, B1); PG8_BAR; PG8_SCHED;
;             PG8_LDA(At, 0, 1); PG8_STAGE(PG8_SB(0, 0), b2, voffB); PG8_STAGE(PG8_SB(0, 1), b2 + hstepB, voffB); PG8_STAGE(PG8_SA(0, 0), a2, voffA);
;             PG8_WAIT_V(8); PG8_WAIT_L(0); PG8_BAR; PG8_MMA(1, 0, At, B0); PG8_MMA(1, 1, At, B1); PG8_BAR; PG8_SCHED;
.LBB0_358:
	s_add_u32 s0, s52, 0xfffc0080
	s_addc_u32 s6, s53, -1
	s_add_i32 s26, 0, 0x10000
	s_cmp_eq_u32 s54, 12
	s_cselect_b32 s15, s9, s6
	s_cselect_b32 s14, s13, s0
	s_cselect_b32 s7, s21, s43
	s_cselect_b32 s6, s23, s33
	s_add_i32 s0, 0, 0x14000
	v_add_u32_e32 v140, s26, v186
	v_add_u32_e32 v168, s0, v186
	ds_read_b128 v[128:131], v140
	ds_read_b128 v[132:135], v140 offset:1024
	ds_read_b128 v[136:139], v140 offset:2048
	ds_read_b128 v[140:143], v140 offset:3072
	ds_read_b128 v[144:147], v168
	ds_read_b128 v[148:151], v168 offset:1024
	ds_read_b128 v[152:155], v168 offset:2048
	ds_read_b128 v[168:171], v168 offset:3072
	v_lshl_add_u64 v[226:227], s[52:53], 0, v[164:165]
	s_add_i32 m0, s51, 0xc000
	ds_read_b128 v[172:175], v196
	ds_read_b128 v[198:201], v196 offset:1024
	ds_read_b128 v[202:205], v196 offset:2048
	ds_read_b128 v[206:209], v196 offset:3072
	ds_read_b128 v[210:213], v196 offset:4096
	ds_read_b128 v[214:217], v196 offset:5120
	ds_read_b128 v[218:221], v196 offset:6144
	ds_read_b128 v[222:225], v196 offset:7168
	global_load_lds_dwordx4 v[226:227], off
	v_lshl_add_u64 v[226:227], s[52:53], 0, v[166:167]
	s_add_i32 m0, s51, 0xe000
	s_nop 0
	global_load_lds_dwordx4 v[226:227], off
	s_waitcnt vmcnt(8)
	s_waitcnt lgkmcnt(0)
	s_barrier
	s_waitcnt lgkmcnt(0)
	v_mfma_f32_16x16x32_bf16 v[124:127], v[128:131], v[172:175], v[124:127]
	v_mfma_f32_16x16x32_bf16 v[120:123], v[136:139], v[172:175], v[120:123]
	v_mfma_f32_16x16x32_bf16 v[108:111], v[128:131], v[202:205], v[108:111]
	v_mfma_f32_16x16x32_bf16 v[104:107], v[136:139], v[202:205], v[104:107]
	v_mfma_f32_16x16x32_bf16 v[92:95], v[128:131], v[210:213], v[92:95]
	v_mfma_f32_16x16x32_bf16 v[88:91], v[136:139], v[210:213], v[88:91]
	v_mfma_f32_16x16x32_bf16 v[76:79], v[128:131], v[218:221], v[76:79]
	v_mfma_f32_16x16x32_bf16 v[72:75], v[136:139], v[218:221], v[72:75]
	v_mfma_f32_16x16x32_bf16 v[124:127], v[132:135], v[198:201], v[124:127]
	v_mfma_f32_16x16x32_bf16 v[120:123], v[140:143], v[198:201], v[120:123]
	v_mfma_f32_16x16x32_bf16 v[108:111], v[132:135], v[206:209], v[108:111]
	v_mfma_f32_16x16x32_bf16 v[104:107], v[140:143], v[206:209], v[104:107]
	v_mfma_f32_16x16x32_bf16 v[92:95], v[132:135], v[214:217], v[92:95]
	v_mfma_f32_16x16x32_bf16 v[88:91], v[140:143], v[214:217], v[88:91]
	v_mfma_f32_16x16x32_bf16 v[76:79], v[132:135], v[222:225], v[76:79]
	v_mfma_f32_16x16x32_bf16 v[72:75], v[140:143], v[222:225], v[72:75]
	v_mfma_f32_16x16x32_bf16 v[116:119], v[144:147], v[172:175], v[116:119]
	v_mfma_f32_16x16x32_bf16 v[112:115], v[152:155], v[172:175], v[112:115]
	v_mfma_f32_16x16x32_bf16 v[100:103], v[144:147], v[202:205], v[100:103]
	v_mfma_f32_16x16x32_bf16 v[96:99], v[152:155], v[202:205], v[96:99]
	v_mfma_f32_16x16x32_bf16 v[84:87], v[144:147], v[210:213], v[84:87]
	v_mfma_f32_16x16x32_bf16 v[80:83], v[152:155], v[210:213], v[80:83]
	v_mfma_f32_16x16x32_bf16 v[68:71], v[144:147], v[218:221], v[68:71]
	v_mfma_f32_16x16x32_bf16 v[64:67], v[152:155], v[218:221], v[64:67]
	v_mfma_f32_16x16x32_bf16 v[116:119], v[148:151], v[198:201], v[116:119]
	v_mfma_f32_16x16x32_bf16 v[112:115], v[168:171], v[198:201], v[112:115]
	v_mfma_f32_16x16x32_bf16 v[100:103], v[148:151], v[206:209], v[100:103]
	v_mfma_f32_16x16x32_bf16 v[96:99], v[168:171], v[206:209], v[96:99]
	v_mfma_f32_16x16x32_bf16 v[84:87], v[148:151], v[214:217], v[84:87]
	v_mfma_f32_16x16x32_bf16 v[80:83], v[168:171], v[214:217], v[80:83]
	v_mfma_f32_16x16x32_bf16 v[68:71], v[148:151], v[222:225], v[68:71]
	v_mfma_f32_16x16x32_bf16 v[64:67], v[168:171], v[222:225], v[64:67]
	s_barrier
	s_add_i32 s26, s26, s20
	v_lshl_add_u64 v[226:227], s[6:7], 0, v[160:161]
	s_mov_b32 m0, s26
	ds_read_b128 v[172:175], v196 offset:16384
	ds_read_b128 v[198:201], v196 offset:17408
	ds_read_b128 v[202:205], v196 offset:18432
	ds_read_b128 v[206:209], v196 offset:19456
	ds_read_b128 v[210:213], v196 offset:20480
	ds_read_b128 v[214:217], v196 offset:21504
	ds_read_b128 v[218:221], v196 offset:22528
	ds_read_b128 v[222:225], v196 offset:23552
	global_load_lds_dwordx4 v[226:227], off
	s_add_i32 m0, s26, 0x2000
	s_add_u32 s78, s6, 0x40000
	v_lshl_add_u64 v[228:229], s[6:7], 0, v[162:163]
	s_addc_u32 s79, s7, 0
	s_add_i32 s0, s0, s20
	global_load_lds_dwordx4 v[228:229], off
	v_lshl_add_u64 v[230:231], s[78:79], 0, v[160:161]
	s_mov_b32 m0, s0
	v_lshl_add_u64 v[232:233], s[14:15], 0, v[158:159]
	global_load_lds_dwordx4 v[230:231], off
	v_lshl_add_u64 v[230:231], s[78:79], 0, v[162:163]
	s_add_i32 m0, s0, 0x2000
	s_nop 0
	global_load_lds_dwordx4 v[230:231], off
	v_lshl_add_u64 v[230:231], s[14:15], 0, v[156:157]
	s_mov_b32 m0, s51
	s_nop 0
	global_load_lds_dwordx4 v[230:231], off
	s_mov_b32 m0, s56
	s_nop 0
	global_load_lds_dwordx4 v[232:233], off
	s_waitcnt vmcnt(8)
	s_waitcnt lgkmcnt(0)
	s_barrier
; #define PG8_STAGE(bufoff, gbase, voff) do { _Pragma("unroll") for (int _i = 0; _i < 2; ++_i) \
;         __builtin_amdgcn_global_load_lds((const unsigned*)((const char*)(gbase) + (voff)[_i]), (LAS unsigned*)(lds + (bufoff) + ldsw + _i * 8192), 16, 0, 0); } while (0)
; #define PG8_LDA(dst, b, h) do { _Pragma("unroll") for (int m = 0; m < 4; ++m) _Pragma("unroll") for (int k = 0; k < 2; ++k) dst[m][k] = *(const LAS bf16x8*)(lds + PG8_SA(b, h) + aoff + m * 2048 + k * 1024); } while (0)
; #define PG8_LDB(dst, b, h) do { _Pragma("unroll") for (int n = 0; n < 2; ++n) _Pragma("unroll") for (int k = 0; k < 2; ++k) dst[n][k] = *(const LAS bf16x8*)(lds + PG8_SB(b, h) + boff + n * 2048 + k * 1024); } while (0)
; #define PG8_MMA(ai, bj, At, Bt) do { __builtin_amdgcn_s_setprio(1); _Pragma("unroll") for (int m = 0; m < 4; ++m) _Pragma("unroll") for (int n = 0; n < 2; ++n) _Pragma("unroll") for (int k = 0; k < 2; ++k) \
;         acc[ai][bj][m][n] = __builtin_amdgcn_mfma_f32_16x16x32_bf16(Bt[n][k], At[m][k], acc[ai][bj][m][n], 0, 0, 0); __builtin_amdgcn_s_setprio(0); } while (0)
; #define PG8_WAIT_V(n) asm volatile("s_waitcnt vmcnt(" #n ")" ::: "memory")
; #define PG8_WAIT_L(n) asm volatile("s_waitcnt lgkmcnt(" #n ")" ::: "memory")
; #define PG8_BAR __builtin_amdgcn_s_barrier()
; #define PG8_SCHED __builtin_amdgcn_sched_barrier(0)
; template <class Epi, class Sched>
; __device__ __forceinline__ void gemm_phase(LAS unsigned char* lds, const Gemm g, const Sched& S, const Epi& E) {
;     ...
;             PG8_WAIT_V(8); PG8_WAIT_L(0); PG8_BAR; PG8_MMA(1, 0, At, B0); PG8_MMA(1, 1, At, B1); PG8_BAR; PG8_SCHED;
;             PG8_LDB(B0, 1, 0); PG8_LDB(B1, 1, 1); PG8_SCHED; PG8_LDA(At, 1, 0); PG8_STAGE(PG8_SA(0, 1), a2 + hstepA, voffA);
;             PG8_WAIT_V(8); PG8_WAIT_L(0); PG8_BAR; PG8_MMA(0, 0, At, B0); PG8_MMA(0, 1, At, B1); PG8_BAR; PG8_SCHED;
	s_waitcnt lgkmcnt(0)
	v_mfma_f32_16x16x32_bf16 v[60:63], v[128:131], v[172:175], v[60:63]
	v_mfma_f32_16x16x32_bf16 v[56:59], v[136:139], v[172:175], v[56:59]
	v_mfma_f32_16x16x32_bf16 v[44:47], v[128:131], v[202:205], v[44:47]
	v_mfma_f32_16x16x32_bf16 v[40:43], v[136:139], v[202:205], v[40:43]
	v_mfma_f32_16x16x32_bf16 v[28:31], v[128:131], v[210:213], v[28:31]
	v_mfma_f32_16x16x32_bf16 v[24:27], v[136:139], v[210:213], v[24:27]
	v_mfma_f32_16x16x32_bf16 v[12:15], v[128:131], v[218:221], v[12:15]
	v_mfma_f32_16x16x32_bf16 v[8:11], v[136:139], v[218:221], v[8:11]
	v_mfma_f32_16x16x32_bf16 v[60:63], v[132:135], v[198:201], v[60:63]
	v_mfma_f32_16x16x32_bf16 v[56:59], v[140:143], v[198:201], v[56:59]
	v_mfma_f32_16x16x32_bf16 v[44:47], v[132:135], v[206:209], v[44:47]
	v_mfma_f32_16x16x32_bf16 v[40:43], v[140:143], v[206:209], v[40:43]
	v_mfma_f32_16x16x32_bf16 v[28:31], v[132:135], v[214:217], v[28:31]
	v_mfma_f32_16x16x32_bf16 v[24:27], v[140:143], v[214:217], v[24:27]
	v_mfma_f32_16x16x32_bf16 v[12:15], v[132:135], v[222:225], v[12:15]
	v_mfma_f32_16x16x32_bf16 v[8:11], v[140:143], v[222:225], v[8:11]
	v_mfma_f32_16x16x32_bf16 v[52:55], v[144:147], v[172:175], v[52:55]
	v_mfma_f32_16x16x32_bf16 v[48:51], v[152:155], v[172:175], v[48:51]
	v_mfma_f32_16x16x32_bf16 v[36:39], v[144:147], v[202:205], v[36:39]
	v_mfma_f32_16x16x32_bf16 v[32:35], v[152:155], v[202:205], v[32:35]
	v_mfma_f32_16x16x32_bf16 v[20:23], v[144:147], v[210:213], v[20:23]
	v_mfma_f32_16x16x32_bf16 v[16:19], v[152:155], v[210:213], v[16:19]
	v_mfma_f32_16x16x32_bf16 v[4:7], v[144:147], v[218:221], v[4:7]
	v_mfma_f32_16x16x32_bf16 v[0:3], v[152:155], v[218:221], v[0:3]
	v_mfma_f32_16x16x32_bf16 v[52:55], v[148:151], v[198:201], v[52:55]
	v_mfma_f32_16x16x32_bf16 v[48:51], v[168:171], v[198:201], v[48:51]
	v_mfma_f32_16x16x32_bf16 v[36:39], v[148:151], v[206:209], v[36:39]
	v_mfma_f32_16x16x32_bf16 v[32:35], v[168:171], v[206:209], v[32:35]
	v_mfma_f32_16x16x32_bf16 v[20:23], v[148:151], v[214:217], v[20:23]
	v_mfma_f32_16x16x32_bf16 v[16:19], v[168:171], v[214:217], v[16:19]
	v_mfma_f32_16x16x32_bf16 v[4:7], v[148:151], v[222:225], v[4:7]
	v_mfma_f32_16x16x32_bf16 v[0:3], v[168:171], v[222:225], v[0:3]
	s_barrier
	s_add_i32 s0, 0, 0x18000
	s_add_i32 s26, 0, 0x1c000
	v_add_u32_e32 v140, s0, v186
	v_add_u32_e32 v168, s26, v186
	ds_read_b128 v[128:131], v140
	ds_read_b128 v[132:135], v140 offset:1024
	ds_read_b128 v[136:139], v140 offset:2048
	ds_read_b128 v[140:143], v140 offset:3072
	ds_read_b128 v[144:147], v168
	ds_read_b128 v[148:151], v168 offset:1024
	ds_read_b128 v[152:155], v168 offset:2048
	ds_read_b128 v[168:171], v168 offset:3072
	s_add_u32 s14, s14, 0x40000
	s_addc_u32 s15, s15, 0
	s_mov_b32 m0, s57
	v_lshl_add_u64 v[234:235], s[14:15], 0, v[156:157]
	ds_read_b128 v[172:175], v196 offset:32768
	ds_read_b128 v[198:201], v196 offset:33792
	ds_read_b128 v[202:205], v196 offset:34816
	ds_read_b128 v[206:209], v196 offset:35840
	ds_read_b128 v[210:213], v196 offset:36864
	ds_read_b128 v[214:217], v196 offset:37888
	ds_read_b128 v[218:221], v196 offset:38912
	ds_read_b128 v[222:225], v196 offset:39936
	global_load_lds_dwordx4 v[234:235], off
	v_lshl_add_u64 v[234:235], s[14:15], 0, v[158:159]
	s_mov_b32 m0, s68
	s_nop 0
	global_load_lds_dwordx4 v[234:235], off
	s_waitcnt vmcnt(8)
	s_waitcnt lgkmcnt(0)
	s_barrier
	s_waitcnt lgkmcnt(0)
	v_mfma_f32_16x16x32_bf16 v[124:127], v[128:131], v[172:175], v[124:127]
	v_mfma_f32_16x16x32_bf16 v[120:123], v[136:139], v[172:175], v[120:123]
	v_mfma_f32_16x16x32_bf16 v[108:111], v[128:131], v[202:205], v[108:111]
	v_mfma_f32_16x16x32_bf16 v[104:107], v[136:139], v[202:205], v[104:107]
	v_mfma_f32_16x16x32_bf16 v[92:95], v[128:131], v[210:213], v[92:95]
	v_mfma_f32_16x16x32_bf16 v[88:91], v[136:139], v[210:213], v[88:91]
	v_mfma_f32_16x16x32_bf16 v[76:79], v[128:131], v[218:221], v[76:79]
	v_mfma_f32_16x16x32_bf16 v[72:75], v[136:139], v[218:221], v[72:75]
	v_mfma_f32_16x16x32_bf16 v[124:127], v[132:135], v[198:201], v[124:127]
	v_mfma_f32_16x16x32_bf16 v[120:123], v[140:143], v[198:201], v[120:123]
	v_mfma_f32_16x16x32_bf16 v[108:111], v[132:135], v[206:209], v[108:111]
	v_mfma_f32_16x16x32_bf16 v[104:107], v[140:143], v[206:209], v[104:107]
	v_mfma_f32_16x16x32_bf16 v[92:95], v[132:135], v[214:217], v[92:95]
	v_mfma_f32_16x16x32_bf16 v[88:91], v[140:143], v[214:217], v[88:91]
	v_mfma_f32_16x16x32_bf16 v[76:79], v[132:135], v[222:225], v[76:79]
	v_mfma_f32_16x16x32_bf16 v[72:75], v[140:143], v[222:225], v[72:75]
	v_mfma_f32_16x16x32_bf16 v[116:119], v[144:147], v[172:175], v[116:119]
	v_mfma_f32_16x16x32_bf16 v[112:115], v[152:155], v[172:175], v[112:115]
	v_mfma_f32_16x16x32_bf16 v[100:103], v[144:147], v[202:205], v[100:103]
	v_mfma_f32_16x16x32_bf16 v[96:99], v[152:155], v[202:205], v[96:99]
	v_mfma_f32_16x16x32_bf16 v[84:87], v[144:147], v[210:213], v[84:87]
	v_mfma_f32_16x16x32_bf16 v[80:83], v[152:155], v[210:213], v[80:83]
	v_mfma_f32_16x16x32_bf16 v[68:71], v[144:147], v[218:221], v[68:71]
	v_mfma_f32_16x16x32_bf16 v[64:67], v[152:155], v[218:221], v[64:67]
	v_mfma_f32_16x16x32_bf16 v[116:119], v[148:151], v[198:201], v[116:119]
	v_mfma_f32_16x16x32_bf16 v[112:115], v[168:171], v[198:201], v[112:115]
	v_mfma_f32_16x16x32_bf16 v[100:103], v[148:151], v[206:209], v[100:103]
	v_mfma_f32_16x16x32_bf16 v[96:99], v[168:171], v[206:209], v[96:99]
	v_mfma_f32_16x16x32_bf16 v[84:87], v[148:151], v[214:217], v[84:87]
	v_mfma_f32_16x16x32_bf16 v[80:83], v[168:171], v[214:217], v[80:83]
	v_mfma_f32_16x16x32_bf16 v[68:71], v[148:151], v[222:225], v[68:71]
	v_mfma_f32_16x16x32_bf16 v[64:67], v[168:171], v[222:225], v[64:67]
	s_barrier
; #define PG8_STAGE(bufoff, gbase, voff) do { _Pragma("unroll") for (int _i = 0; _i < 2; ++_i) \
;         __builtin_amdgcn_global_load_lds((const unsigned*)((const char*)(gbase) + (voff)[_i]), (LAS unsigned*)(lds + (bufoff) + ldsw + _i * 8192), 16, 0, 0); } while (0)
; #define PG8_LDA(dst, b, h) do { _Pragma("unroll") for (int m = 0; m < 4; ++m) _Pragma("unroll") for (int k = 0; k < 2; ++k) dst[m][k] = *(const LAS bf16x8*)(lds + PG8_SA(b, h) + aoff + m * 2048 + k * 1024); } while (0)
; #define PG8_MMA(ai, bj, At, Bt) do { __builtin_amdgcn_s_setprio(1); _Pragma("unroll") for (int m = 0; m < 4; ++m) _Pragma("unroll") for (int n = 0; n < 2; ++n) _Pragma("unroll") for (int k = 0; k < 2; ++k) \
;         acc[ai][bj][m][n] = __builtin_amdgcn_mfma_f32_16x16x32_bf16(Bt[n][k], At[m][k], acc[ai][bj][m][n], 0, 0, 0); __builtin_amdgcn_s_setprio(0); } while (0)
; #define PG8_WAIT_V(n) asm volatile("s_waitcnt vmcnt(" #n ")" ::: "memory")
; #define PG8_WAIT_L(n) asm volatile("s_waitcnt lgkmcnt(" #n ")" ::: "memory")
; #define PG8_BAR __builtin_amdgcn_s_barrier()
; #define PG8_SCHED __builtin_amdgcn_sched_barrier(0)
; template <class Epi, class Sched>
; __device__ __forceinline__ void gemm_phase(LAS unsigned char* lds, const Gemm g, const Sched& S, const Epi& E) {
;     ...
;             PG8_LDA(At, 1, 1); PG8_STAGE(PG8_SB(1, 0), b3, voffB); PG8_STAGE(PG8_SB(1, 1), b3 + hstepB, voffB); PG8_STAGE(PG8_SA(1, 0), a3, voffA);
;             PG8_WAIT_V(8); PG8_WAIT_L(0); PG8_BAR; PG8_MMA(1, 0, At, B0); PG8_MMA(1, 1, At, B1); PG8_BAR; PG8_SCHED;
;         }
;         if (wr == 0) PG8_BAR;
	s_add_i32 s0, s0, s20
	v_lshl_add_u64 v[226:227], v[226:227], 0, s[30:31]
	s_mov_b32 m0, s0
	ds_read_b128 v[172:175], v196 offset:49152
	ds_read_b128 v[198:201], v196 offset:50176
	ds_read_b128 v[202:205], v196 offset:51200
	ds_read_b128 v[206:209], v196 offset:52224
	ds_read_b128 v[210:213], v196 offset:53248
	ds_read_b128 v[214:217], v196 offset:54272
	ds_read_b128 v[218:221], v196 offset:55296
	ds_read_b128 v[222:225], v196 offset:56320
	global_load_lds_dwordx4 v[226:227], off
	s_add_i32 m0, s0, 0x2000
	s_add_u32 s6, s6, 0x40080
	v_lshl_add_u64 v[226:227], v[228:229], 0, s[30:31]
	s_addc_u32 s7, s7, 0
	s_add_i32 s0, s26, s20
	global_load_lds_dwordx4 v[226:227], off
	v_lshl_add_u64 v[226:227], s[6:7], 0, v[160:161]
	s_mov_b32 m0, s0
	s_nop 0
	global_load_lds_dwordx4 v[226:227], off
	v_lshl_add_u64 v[226:227], s[6:7], 0, v[162:163]
	s_add_i32 m0, s0, 0x2000
	s_nop 0
	global_load_lds_dwordx4 v[226:227], off
	v_lshl_add_u64 v[226:227], v[230:231], 0, s[30:31]
	s_mov_b32 m0, s24
	s_nop 0
	global_load_lds_dwordx4 v[226:227], off
	v_lshl_add_u64 v[226:227], v[232:233], 0, s[30:31]
	s_mov_b32 m0, s25
	s_nop 0
	global_load_lds_dwordx4 v[226:227], off
	s_waitcnt vmcnt(8)
	s_waitcnt lgkmcnt(0)
	s_barrier
	s_waitcnt lgkmcnt(0)
	v_mfma_f32_16x16x32_bf16 v[60:63], v[128:131], v[172:175], v[60:63]
	v_mfma_f32_16x16x32_bf16 v[56:59], v[136:139], v[172:175], v[56:59]
	v_mfma_f32_16x16x32_bf16 v[44:47], v[128:131], v[202:205], v[44:47]
	v_mfma_f32_16x16x32_bf16 v[40:43], v[136:139], v[202:205], v[40:43]
	v_mfma_f32_16x16x32_bf16 v[28:31], v[128:131], v[210:213], v[28:31]
	v_mfma_f32_16x16x32_bf16 v[24:27], v[136:139], v[210:213], v[24:27]
	v_mfma_f32_16x16x32_bf16 v[12:15], v[128:131], v[218:221], v[12:15]
	v_mfma_f32_16x16x32_bf16 v[8:11], v[136:139], v[218:221], v[8:11]
	v_mfma_f32_16x16x32_bf16 v[60:63], v[132:135], v[198:201], v[60:63]
	v_mfma_f32_16x16x32_bf16 v[56:59], v[140:143], v[198:201], v[56:59]
	v_mfma_f32_16x16x32_bf16 v[44:47], v[132:135], v[206:209], v[44:47]
	v_mfma_f32_16x16x32_bf16 v[40:43], v[140:143], v[206:209], v[40:43]
	v_mfma_f32_16x16x32_bf16 v[28:31], v[132:135], v[214:217], v[28:31]
	v_mfma_f32_16x16x32_bf16 v[24:27], v[140:143], v[214:217], v[24:27]
	v_mfma_f32_16x16x32_bf16 v[12:15], v[132:135], v[222:225], v[12:15]
	v_mfma_f32_16x16x32_bf16 v[8:11], v[140:143], v[222:225], v[8:11]
	v_mfma_f32_16x16x32_bf16 v[52:55], v[144:147], v[172:175], v[52:55]
	v_mfma_f32_16x16x32_bf16 v[48:51], v[152:155], v[172:175], v[48:51]
	v_mfma_f32_16x16x32_bf16 v[36:39], v[144:147], v[202:205], v[36:39]
	v_mfma_f32_16x16x32_bf16 v[32:35], v[152:155], v[202:205], v[32:35]
	v_mfma_f32_16x16x32_bf16 v[20:23], v[144:147], v[210:213], v[20:23]
	v_mfma_f32_16x16x32_bf16 v[16:19], v[152:155], v[210:213], v[16:19]
	v_mfma_f32_16x16x32_bf16 v[4:7], v[144:147], v[218:221], v[4:7]
	v_mfma_f32_16x16x32_bf16 v[0:3], v[152:155], v[218:221], v[0:3]
	v_mfma_f32_16x16x32_bf16 v[52:55], v[148:151], v[198:201], v[52:55]
	v_mfma_f32_16x16x32_bf16 v[48:51], v[168:171], v[198:201], v[48:51]
	v_mfma_f32_16x16x32_bf16 v[36:39], v[148:151], v[206:209], v[36:39]
	v_mfma_f32_16x16x32_bf16 v[32:35], v[168:171], v[206:209], v[32:35]
	v_mfma_f32_16x16x32_bf16 v[20:23], v[148:151], v[214:217], v[20:23]
	v_mfma_f32_16x16x32_bf16 v[16:19], v[168:171], v[214:217], v[16:19]
	v_mfma_f32_16x16x32_bf16 v[4:7], v[148:151], v[222:225], v[4:7]
	v_mfma_f32_16x16x32_bf16 v[0:3], v[168:171], v[222:225], v[0:3]
	s_barrier
	s_add_i32 s54, s54, 2
	s_add_u32 s52, s52, 0x100
	s_addc_u32 s53, s53, 0
	s_add_u32 s33, s33, 0x100
	s_addc_u32 s43, s43, 0
	s_cmp_gt_u32 s54, 13
	s_cbranch_scc0 .LBB0_358
	s_and_b64 vcc, exec, s[18:19]
	s_cbranch_vccz .LBB0_361
	s_barrier

; #define PG8_STAGE(bufoff, gbase, voff) do { _Pragma("unroll") for (int _i = 0; _i < 2; ++_i) \
;         __builtin_amdgcn_global_load_lds((const unsigned*)((const char*)(gbase) + (voff)[_i]), (LAS unsigned*)(lds + (bufoff) + ldsw + _i * 8192), 16, 0, 0); } while (0)
; #define PG8_LDA(dst, b, h) do { _Pragma("unroll") for (int m = 0; m < 4; ++m) _Pragma("unroll") for (int k = 0; k < 2; ++k) dst[m][k] = *(const LAS bf16x8*)(lds + PG8_SA(b, h) + aoff + m * 2048 + k * 1024); } while (0)
; #define PG8_LDB(dst, b, h) do { _Pragma("unroll") for (int n = 0; n < 2; ++n) _Pragma("unroll") for (int k = 0; k < 2; ++k) dst[n][k] = *(const LAS bf16x8*)(lds + PG8_SB(b, h) + boff + n * 2048 + k * 1024); } while (0)
; #define PG8_MMA(ai, bj, At, Bt) do { __builtin_amdgcn_s_setprio(1); _Pragma("unroll") for (int m = 0; m < 4; ++m) _Pragma("unroll") for (int n = 0; n < 2; ++n) _Pragma("unroll") for (int k = 0; k < 2; ++k) \
;         acc[ai][bj][m][n] = __builtin_amdgcn_mfma_f32_16x16x32_bf16(Bt[n][k], At[m][k], acc[ai][bj][m][n], 0, 0, 0); __builtin_amdgcn_s_setprio(0); } while (0)
; #define PG8_BAR __builtin_amdgcn_s_barrier()
; template <class Epi, class Sched>
; __device__ __forceinline__ void gemm_phase(LAS unsigned char* lds, const Gemm g, const Sched& S, const Epi& E) {
;     ...
;         const bool has_next = S.next(ui + 1, nxt);
;         const char* nA = has_next ? (const char*)g.A + (size_t)nxt.pm * tstepA + (size_t)nxt.pn * apn : cA; const char* nB = has_next ? (const char*)g.Bt + (size_t)nxt.pn * tstepB : cB;
;         for (int t = 0; t < nt; t += 2) {
;             const bool last = (t == nt - 2);
;             const char* a1 = cA + (size_t)(t + 1) * kstep;
;             const char* a2 = last ? nA : cA + (size_t)(t + 2) * kstep; const char* b2 = last ? nB : cB + (size_t)(t + 2) * kstep;
;             const char* a3 = a2 + kstep; const char* b3 = b2 + kstep;
;             PG8_LDB(B0, 0, 0); PG8_LDB(B1, 0, 1); PG8_SCHED; PG8_LDA(At, 0, 0); PG8_STAGE(PG8_SA(1, 1), a1 + hstepA, voffA);
;             PG8_WAIT_V(8); PG8_WAIT_L(0); PG8_BAR; PG8_MMA(0, 0, At, B0); PG8_MMA(0, 1, At, B1); PG8_BAR; PG8_SCHED;
;             PG8_LDA(At, 0, 1); PG8_STAGE(PG8_SB(0, 0), b2, voffB); PG8_STAGE(PG8_SB(0, 1), b2 + hstepB, voffB); PG8_STAGE(PG8_SA(0, 0), a2, voffA);
;             PG8_WAIT_V(8); PG8_WAIT_L(0); PG8_BAR; PG8_MMA(1, 0, At, B0); PG8_MMA(1, 1, At, B1); PG8_BAR; PG8_SCHED;
.LBB0_807:
	s_add_u32 s46, s44, 0x100
	s_addc_u32 s47, s45, 0
	s_add_i32 s0, 0, 0x10000
	s_cmp_eq_u32 s54, 40
	s_cselect_b32 s15, s23, s47
	s_cselect_b32 s14, s22, s46
	s_cselect_b32 s7, s35, s53
	s_cselect_b32 s6, s34, s33
	s_add_i32 s26, 0, 0x14000
	v_add_u32_e32 v140, s0, v186
	v_add_u32_e32 v168, s26, v186
	ds_read_b128 v[128:131], v140
	ds_read_b128 v[132:135], v140 offset:1024
	ds_read_b128 v[136:139], v140 offset:2048
	ds_read_b128 v[140:143], v140 offset:3072
	ds_read_b128 v[144:147], v168
	ds_read_b128 v[148:151], v168 offset:1024
	ds_read_b128 v[152:155], v168 offset:2048
	ds_read_b128 v[168:171], v168 offset:3072
	v_lshl_add_u64 v[226:227], s[44:45], 0, v[164:165]
	s_add_i32 m0, s49, 0xc000
	ds_read_b128 v[172:175], v196
	ds_read_b128 v[198:201], v196 offset:1024
	ds_read_b128 v[202:205], v196 offset:2048
	ds_read_b128 v[206:209], v196 offset:3072
	ds_read_b128 v[210:213], v196 offset:4096
	ds_read_b128 v[214:217], v196 offset:5120
	ds_read_b128 v[218:221], v196 offset:6144
	ds_read_b128 v[222:225], v196 offset:7168
	global_load_lds_dwordx4 v[226:227], off
	v_lshl_add_u64 v[226:227], s[44:45], 0, v[166:167]
	s_add_i32 m0, s49, 0xe000
	s_nop 0
	global_load_lds_dwordx4 v[226:227], off
	s_waitcnt vmcnt(8)
	s_waitcnt lgkmcnt(0)
	s_barrier
	s_waitcnt lgkmcnt(0)
	v_mfma_f32_16x16x32_bf16 v[124:127], v[128:131], v[172:175], v[124:127]
	v_mfma_f32_16x16x32_bf16 v[120:123], v[136:139], v[172:175], v[120:123]
	v_mfma_f32_16x16x32_bf16 v[108:111], v[128:131], v[202:205], v[108:111]
	v_mfma_f32_16x16x32_bf16 v[104:107], v[136:139], v[202:205], v[104:107]
	v_mfma_f32_16x16x32_bf16 v[92:95], v[128:131], v[210:213], v[92:95]
	v_mfma_f32_16x16x32_bf16 v[88:91], v[136:139], v[210:213], v[88:91]
	v_mfma_f32_16x16x32_bf16 v[76:79], v[128:131], v[218:221], v[76:79]
	v_mfma_f32_16x16x32_bf16 v[72:75], v[136:139], v[218:221], v[72:75]
	v_mfma_f32_16x16x32_bf16 v[124:127], v[132:135], v[198:201], v[124:127]
	v_mfma_f32_16x16x32_bf16 v[120:123], v[140:143], v[198:201], v[120:123]
	v_mfma_f32_16x16x32_bf16 v[108:111], v[132:135], v[206:209], v[108:111]
	v_mfma_f32_16x16x32_bf16 v[104:107], v[140:143], v[206:209], v[104:107]
	v_mfma_f32_16x16x32_bf16 v[92:95], v[132:135], v[214:217], v[92:95]
	v_mfma_f32_16x16x32_bf16 v[88:91], v[140:143], v[214:217], v[88:91]
	v_mfma_f32_16x16x32_bf16 v[76:79], v[132:135], v[222:225], v[76:79]
	v_mfma_f32_16x16x32_bf16 v[72:75], v[140:143], v[222:225], v[72:75]
	v_mfma_f32_16x16x32_bf16 v[116:119], v[144:147], v[172:175], v[116:119]
	v_mfma_f32_16x16x32_bf16 v[112:115], v[152:155], v[172:175], v[112:115]
	v_mfma_f32_16x16x32_bf16 v[100:103], v[144:147], v[202:205], v[100:103]
	v_mfma_f32_16x16x32_bf16 v[96:99], v[152:155], v[202:205], v[96:99]
	v_mfma_f32_16x16x32_bf16 v[84:87], v[144:147], v[210:213], v[84:87]
	v_mfma_f32_16x16x32_bf16 v[80:83], v[152:155], v[210:213], v[80:83]
	v_mfma_f32_16x16x32_bf16 v[68:71], v[144:147], v[218:221], v[68:71]
	v_mfma_f32_16x16x32_bf16 v[64:67], v[152:155], v[218:221], v[64:67]
	v_mfma_f32_16x16x32_bf16 v[116:119], v[148:151], v[198:201], v[116:119]
	v_mfma_f32_16x16x32_bf16 v[112:115], v[168:171], v[198:201], v[112:115]
	v_mfma_f32_16x16x32_bf16 v[100:103], v[148:151], v[206:209], v[100:103]
	v_mfma_f32_16x16x32_bf16 v[96:99], v[168:171], v[206:209], v[96:99]
	v_mfma_f32_16x16x32_bf16 v[84:87], v[148:151], v[214:217], v[84:87]
	v_mfma_f32_16x16x32_bf16 v[80:83], v[168:171], v[214:217], v[80:83]
	v_mfma_f32_16x16x32_bf16 v[68:71], v[148:151], v[222:225], v[68:71]
	v_mfma_f32_16x16x32_bf16 v[64:67], v[168:171], v[222:225], v[64:67]
	s_barrier
	s_add_i32 s0, s0, s20
	v_lshl_add_u64 v[226:227], s[6:7], 0, v[160:161]
	s_mov_b32 m0, s0
	ds_read_b128 v[172:175], v196 offset:16384
	ds_read_b128 v[198:201], v196 offset:17408
	ds_read_b128 v[202:205], v196 offset:18432
	ds_read_b128 v[206:209], v196 offset:19456
	ds_read_b128 v[210:213], v196 offset:20480
	ds_read_b128 v[214:217], v196 offset:21504
	ds_read_b128 v[218:221], v196 offset:22528
	ds_read_b128 v[222:225], v196 offset:23552
	global_load_lds_dwordx4 v[226:227], off
	s_add_i32 m0, s0, 0x2000
	s_add_u32 s44, s6, 0xb0000
	v_lshl_add_u64 v[228:229], s[6:7], 0, v[162:163]
	s_addc_u32 s45, s7, 0
	s_add_i32 s0, s26, s20
	global_load_lds_dwordx4 v[228:229], off
	v_lshl_add_u64 v[230:231], s[44:45], 0, v[160:161]
	s_mov_b32 m0, s0
	v_lshl_add_u64 v[232:233], s[14:15], 0, v[158:159]
	global_load_lds_dwordx4 v[230:231], off
	v_lshl_add_u64 v[230:231], s[44:45], 0, v[162:163]
	s_add_i32 m0, s0, 0x2000
	s_nop 0
	global_load_lds_dwordx4 v[230:231], off
	v_lshl_add_u64 v[230:231], s[14:15], 0, v[156:157]
	s_mov_b32 m0, s49
	s_nop 0
	global_load_lds_dwordx4 v[230:231], off
	s_mov_b32 m0, s50
	s_nop 0
	global_load_lds_dwordx4 v[232:233], off
	s_waitcnt vmcnt(8)
	s_waitcnt lgkmcnt(0)
	s_barrier
; #define PG8_STAGE(bufoff, gbase, voff) do { _Pragma("unroll") for (int _i = 0; _i < 2; ++_i) \
;         __builtin_amdgcn_global_load_lds((const unsigned*)((const char*)(gbase) + (voff)[_i]), (LAS unsigned*)(lds + (bufoff) + ldsw + _i * 8192), 16, 0, 0); } while (0)
; #define PG8_LDA(dst, b, h) do { _Pragma("unroll") for (int m = 0; m < 4; ++m) _Pragma("unroll") for (int k = 0; k < 2; ++k) dst[m][k] = *(const LAS bf16x8*)(lds + PG8_SA(b, h) + aoff + m * 2048 + k * 1024); } while (0)
; #define PG8_LDB(dst, b, h) do { _Pragma("unroll") for (int n = 0; n < 2; ++n) _Pragma("unroll") for (int k = 0; k < 2; ++k) dst[n][k] = *(const LAS bf16x8*)(lds + PG8_SB(b, h) + boff + n * 2048 + k * 1024); } while (0)
; #define PG8_MMA(ai, bj, At, Bt) do { __builtin_amdgcn_s_setprio(1); _Pragma("unroll") for (int m = 0; m < 4; ++m) _Pragma("unroll") for (int n = 0; n < 2; ++n) _Pragma("unroll") for (int k = 0; k < 2; ++k) \
;         acc[ai][bj][m][n] = __builtin_amdgcn_mfma_f32_16x16x32_bf16(Bt[n][k], At[m][k], acc[ai][bj][m][n], 0, 0, 0); __builtin_amdgcn_s_setprio(0); } while (0)
; #define PG8_WAIT_V(n) asm volatile("s_waitcnt vmcnt(" #n ")" ::: "memory")
; #define PG8_WAIT_L(n) asm volatile("s_waitcnt lgkmcnt(" #n ")" ::: "memory")
; #define PG8_BAR __builtin_amdgcn_s_barrier()
; #define PG8_SCHED __builtin_amdgcn_sched_barrier(0)
; template <class Epi, class Sched>
; __device__ __forceinline__ void gemm_phase(LAS unsigned char* lds, const Gemm g, const Sched& S, const Epi& E) {
;     ...
;             PG8_WAIT_V(8); PG8_WAIT_L(0); PG8_BAR; PG8_MMA(1, 0, At, B0); PG8_MMA(1, 1, At, B1); PG8_BAR; PG8_SCHED;
;             PG8_LDB(B0, 1, 0); PG8_LDB(B1, 1, 1); PG8_SCHED; PG8_LDA(At, 1, 0); PG8_STAGE(PG8_SA(0, 1), a2 + hstepA, voffA);
;             PG8_WAIT_V(8); PG8_WAIT_L(0); PG8_BAR; PG8_MMA(0, 0, At, B0); PG8_MMA(0, 1, At, B1); PG8_BAR; PG8_SCHED;
	s_waitcnt lgkmcnt(0)
	v_mfma_f32_16x16x32_bf16 v[60:63], v[128:131], v[172:175], v[60:63]
	v_mfma_f32_16x16x32_bf16 v[56:59], v[136:139], v[172:175], v[56:59]
	v_mfma_f32_16x16x32_bf16 v[44:47], v[128:131], v[202:205], v[44:47]
	v_mfma_f32_16x16x32_bf16 v[40:43], v[136:139], v[202:205], v[40:43]
	v_mfma_f32_16x16x32_bf16 v[28:31], v[128:131], v[210:213], v[28:31]
	v_mfma_f32_16x16x32_bf16 v[24:27], v[136:139], v[210:213], v[24:27]
	v_mfma_f32_16x16x32_bf16 v[12:15], v[128:131], v[218:221], v[12:15]
	v_mfma_f32_16x16x32_bf16 v[8:11], v[136:139], v[218:221], v[8:11]
	v_mfma_f32_16x16x32_bf16 v[60:63], v[132:135], v[198:201], v[60:63]
	v_mfma_f32_16x16x32_bf16 v[56:59], v[140:143], v[198:201], v[56:59]
	v_mfma_f32_16x16x32_bf16 v[44:47], v[132:135], v[206:209], v[44:47]
	v_mfma_f32_16x16x32_bf16 v[40:43], v[140:143], v[206:209], v[40:43]
	v_mfma_f32_16x16x32_bf16 v[28:31], v[132:135], v[214:217], v[28:31]
	v_mfma_f32_16x16x32_bf16 v[24:27], v[140:143], v[214:217], v[24:27]
	v_mfma_f32_16x16x32_bf16 v[12:15], v[132:135], v[222:225], v[12:15]
	v_mfma_f32_16x16x32_bf16 v[8:11], v[140:143], v[222:225], v[8:11]
	v_mfma_f32_16x16x32_bf16 v[52:55], v[144:147], v[172:175], v[52:55]
	v_mfma_f32_16x16x32_bf16 v[48:51], v[152:155], v[172:175], v[48:51]
	v_mfma_f32_16x16x32_bf16 v[36:39], v[144:147], v[202:205], v[36:39]
	v_mfma_f32_16x16x32_bf16 v[32:35], v[152:155], v[202:205], v[32:35]
	v_mfma_f32_16x16x32_bf16 v[20:23], v[144:147], v[210:213], v[20:23]
	v_mfma_f32_16x16x32_bf16 v[16:19], v[152:155], v[210:213], v[16:19]
	v_mfma_f32_16x16x32_bf16 v[4:7], v[144:147], v[218:221], v[4:7]
	v_mfma_f32_16x16x32_bf16 v[0:3], v[152:155], v[218:221], v[0:3]
	v_mfma_f32_16x16x32_bf16 v[52:55], v[148:151], v[198:201], v[52:55]
	v_mfma_f32_16x16x32_bf16 v[48:51], v[168:171], v[198:201], v[48:51]
	v_mfma_f32_16x16x32_bf16 v[36:39], v[148:151], v[206:209], v[36:39]
	v_mfma_f32_16x16x32_bf16 v[32:35], v[168:171], v[206:209], v[32:35]
	v_mfma_f32_16x16x32_bf16 v[20:23], v[148:151], v[214:217], v[20:23]
	v_mfma_f32_16x16x32_bf16 v[16:19], v[168:171], v[214:217], v[16:19]
	v_mfma_f32_16x16x32_bf16 v[4:7], v[148:151], v[222:225], v[4:7]
	v_mfma_f32_16x16x32_bf16 v[0:3], v[168:171], v[222:225], v[0:3]
	s_barrier
	s_add_i32 s0, 0, 0x18000
	s_add_i32 s26, 0, 0x1c000
	v_add_u32_e32 v140, s0, v186
	v_add_u32_e32 v168, s26, v186
	ds_read_b128 v[128:131], v140
	ds_read_b128 v[132:135], v140 offset:1024
	ds_read_b128 v[136:139], v140 offset:2048
	ds_read_b128 v[140:143], v140 offset:3072
	ds_read_b128 v[144:147], v168
	ds_read_b128 v[148:151], v168 offset:1024
	ds_read_b128 v[152:155], v168 offset:2048
	ds_read_b128 v[168:171], v168 offset:3072
	s_add_u32 s14, s14, 0xb0000
	s_addc_u32 s15, s15, 0
	s_mov_b32 m0, s51
	v_lshl_add_u64 v[234:235], s[14:15], 0, v[156:157]
	ds_read_b128 v[172:175], v196 offset:32768
	ds_read_b128 v[198:201], v196 offset:33792
	ds_read_b128 v[202:205], v196 offset:34816
	ds_read_b128 v[206:209], v196 offset:35840
	ds_read_b128 v[210:213], v196 offset:36864
	ds_read_b128 v[214:217], v196 offset:37888
	ds_read_b128 v[218:221], v196 offset:38912
	ds_read_b128 v[222:225], v196 offset:39936
	global_load_lds_dwordx4 v[234:235], off
	v_lshl_add_u64 v[234:235], s[14:15], 0, v[158:159]
	s_mov_b32 m0, s52
	s_nop 0
	global_load_lds_dwordx4 v[234:235], off
	s_waitcnt vmcnt(8)
	s_waitcnt lgkmcnt(0)
	s_barrier
	s_waitcnt lgkmcnt(0)
	v_mfma_f32_16x16x32_bf16 v[124:127], v[128:131], v[172:175], v[124:127]
	v_mfma_f32_16x16x32_bf16 v[120:123], v[136:139], v[172:175], v[120:123]
	v_mfma_f32_16x16x32_bf16 v[108:111], v[128:131], v[202:205], v[108:111]
	v_mfma_f32_16x16x32_bf16 v[104:107], v[136:139], v[202:205], v[104:107]
	v_mfma_f32_16x16x32_bf16 v[92:95], v[128:131], v[210:213], v[92:95]
	v_mfma_f32_16x16x32_bf16 v[88:91], v[136:139], v[210:213], v[88:91]
	v_mfma_f32_16x16x32_bf16 v[76:79], v[128:131], v[218:221], v[76:79]
	v_mfma_f32_16x16x32_bf16 v[72:75], v[136:139], v[218:221], v[72:75]
	v_mfma_f32_16x16x32_bf16 v[124:127], v[132:135], v[198:201], v[124:127]
	v_mfma_f32_16x16x32_bf16 v[120:123], v[140:143], v[198:201], v[120:123]
	v_mfma_f32_16x16x32_bf16 v[108:111], v[132:135], v[206:209], v[108:111]
	v_mfma_f32_16x16x32_bf16 v[104:107], v[140:143], v[206:209], v[104:107]
	v_mfma_f32_16x16x32_bf16 v[92:95], v[132:135], v[214:217], v[92:95]
	v_mfma_f32_16x16x32_bf16 v[88:91], v[140:143], v[214:217], v[88:91]
	v_mfma_f32_16x16x32_bf16 v[76:79], v[132:135], v[222:225], v[76:79]
	v_mfma_f32_16x16x32_bf16 v[72:75], v[140:143], v[222:225], v[72:75]
	v_mfma_f32_16x16x32_bf16 v[116:119], v[144:147], v[172:175], v[116:119]
	v_mfma_f32_16x16x32_bf16 v[112:115], v[152:155], v[172:175], v[112:115]
	v_mfma_f32_16x16x32_bf16 v[100:103], v[144:147], v[202:205], v[100:103]
	v_mfma_f32_16x16x32_bf16 v[96:99], v[152:155], v[202:205], v[96:99]
	v_mfma_f32_16x16x32_bf16 v[84:87], v[144:147], v[210:213], v[84:87]
	v_mfma_f32_16x16x32_bf16 v[80:83], v[152:155], v[210:213], v[80:83]
	v_mfma_f32_16x16x32_bf16 v[68:71], v[144:147], v[218:221], v[68:71]
	v_mfma_f32_16x16x32_bf16 v[64:67], v[152:155], v[218:221], v[64:67]
	v_mfma_f32_16x16x32_bf16 v[116:119], v[148:151], v[198:201], v[116:119]
	v_mfma_f32_16x16x32_bf16 v[112:115], v[168:171], v[198:201], v[112:115]
	v_mfma_f32_16x16x32_bf16 v[100:103], v[148:151], v[206:209], v[100:103]
	v_mfma_f32_16x16x32_bf16 v[96:99], v[168:171], v[206:209], v[96:99]
	v_mfma_f32_16x16x32_bf16 v[84:87], v[148:151], v[214:217], v[84:87]
	v_mfma_f32_16x16x32_bf16 v[80:83], v[168:171], v[214:217], v[80:83]
	v_mfma_f32_16x16x32_bf16 v[68:71], v[148:151], v[222:225], v[68:71]
	v_mfma_f32_16x16x32_bf16 v[64:67], v[168:171], v[222:225], v[64:67]
	s_barrier
; #define PG8_STAGE(bufoff, gbase, voff) do { _Pragma("unroll") for (int _i = 0; _i < 2; ++_i) \
;         __builtin_amdgcn_global_load_lds((const unsigned*)((const char*)(gbase) + (voff)[_i]), (LAS unsigned*)(lds + (bufoff) + ldsw + _i * 8192), 16, 0, 0); } while (0)
; #define PG8_LDA(dst, b, h) do { _Pragma("unroll") for (int m = 0; m < 4; ++m) _Pragma("unroll") for (int k = 0; k < 2; ++k) dst[m][k] = *(const LAS bf16x8*)(lds + PG8_SA(b, h) + aoff + m * 2048 + k * 1024); } while (0)
; #define PG8_MMA(ai, bj, At, Bt) do { __builtin_amdgcn_s_setprio(1); _Pragma("unroll") for (int m = 0; m < 4; ++m) _Pragma("unroll") for (int n = 0; n < 2; ++n) _Pragma("unroll") for (int k = 0; k < 2; ++k) \
;         acc[ai][bj][m][n] = __builtin_amdgcn_mfma_f32_16x16x32_bf16(Bt[n][k], At[m][k], acc[ai][bj][m][n], 0, 0, 0); __builtin_amdgcn_s_setprio(0); } while (0)
; #define PG8_WAIT_V(n) asm volatile("s_waitcnt vmcnt(" #n ")" ::: "memory")
; #define PG8_WAIT_L(n) asm volatile("s_waitcnt lgkmcnt(" #n ")" ::: "memory")
; #define PG8_BAR __builtin_amdgcn_s_barrier()
; #define PG8_SCHED __builtin_amdgcn_sched_barrier(0)
; template <class Epi, class Sched>
; __device__ __forceinline__ void gemm_phase(LAS unsigned char* lds, const Gemm g, const Sched& S, const Epi& E) {
;     ...
;             PG8_LDA(At, 1, 1); PG8_STAGE(PG8_SB(1, 0), b3, voffB); PG8_STAGE(PG8_SB(1, 1), b3 + hstepB, voffB); PG8_STAGE(PG8_SA(1, 0), a3, voffA);
;             PG8_WAIT_V(8); PG8_WAIT_L(0); PG8_BAR; PG8_MMA(1, 0, At, B0); PG8_MMA(1, 1, At, B1); PG8_BAR; PG8_SCHED;
;         }
;         if (wr == 0) PG8_BAR;
	s_add_i32 s0, s0, s20
	v_lshl_add_u64 v[226:227], v[226:227], 0, s[30:31]
	s_mov_b32 m0, s0
	ds_read_b128 v[172:175], v196 offset:49152
	ds_read_b128 v[198:201], v196 offset:50176
	ds_read_b128 v[202:205], v196 offset:51200
	ds_read_b128 v[206:209], v196 offset:52224
	ds_read_b128 v[210:213], v196 offset:53248
	ds_read_b128 v[214:217], v196 offset:54272
	ds_read_b128 v[218:221], v196 offset:55296
	ds_read_b128 v[222:225], v196 offset:56320
	global_load_lds_dwordx4 v[226:227], off
	s_add_i32 m0, s0, 0x2000
	s_add_u32 s6, s6, 0xb0080
	v_lshl_add_u64 v[226:227], v[228:229], 0, s[30:31]
	s_addc_u32 s7, s7, 0
	s_add_i32 s0, s26, s20
	global_load_lds_dwordx4 v[226:227], off
	v_lshl_add_u64 v[226:227], s[6:7], 0, v[160:161]
	s_mov_b32 m0, s0
	s_nop 0
	global_load_lds_dwordx4 v[226:227], off
	v_lshl_add_u64 v[226:227], s[6:7], 0, v[162:163]
	s_add_i32 m0, s0, 0x2000
	s_nop 0
	global_load_lds_dwordx4 v[226:227], off
	v_lshl_add_u64 v[226:227], v[230:231], 0, s[30:31]
	s_mov_b32 m0, s24
	s_nop 0
	global_load_lds_dwordx4 v[226:227], off
	v_lshl_add_u64 v[226:227], v[232:233], 0, s[30:31]
	s_mov_b32 m0, s25
	s_nop 0
	global_load_lds_dwordx4 v[226:227], off
	s_waitcnt vmcnt(8)
	s_waitcnt lgkmcnt(0)
	s_barrier
	s_waitcnt lgkmcnt(0)
	v_mfma_f32_16x16x32_bf16 v[60:63], v[128:131], v[172:175], v[60:63]
	v_mfma_f32_16x16x32_bf16 v[56:59], v[136:139], v[172:175], v[56:59]
	v_mfma_f32_16x16x32_bf16 v[44:47], v[128:131], v[202:205], v[44:47]
	v_mfma_f32_16x16x32_bf16 v[40:43], v[136:139], v[202:205], v[40:43]
	v_mfma_f32_16x16x32_bf16 v[28:31], v[128:131], v[210:213], v[28:31]
	v_mfma_f32_16x16x32_bf16 v[24:27], v[136:139], v[210:213], v[24:27]
	v_mfma_f32_16x16x32_bf16 v[12:15], v[128:131], v[218:221], v[12:15]
	v_mfma_f32_16x16x32_bf16 v[8:11], v[136:139], v[218:221], v[8:11]
	v_mfma_f32_16x16x32_bf16 v[60:63], v[132:135], v[198:201], v[60:63]
	v_mfma_f32_16x16x32_bf16 v[56:59], v[140:143], v[198:201], v[56:59]
	v_mfma_f32_16x16x32_bf16 v[44:47], v[132:135], v[206:209], v[44:47]
	v_mfma_f32_16x16x32_bf16 v[40:43], v[140:143], v[206:209], v[40:43]
	v_mfma_f32_16x16x32_bf16 v[28:31], v[132:135], v[214:217], v[28:31]
	v_mfma_f32_16x16x32_bf16 v[24:27], v[140:143], v[214:217], v[24:27]
	v_mfma_f32_16x16x32_bf16 v[12:15], v[132:135], v[222:225], v[12:15]
	v_mfma_f32_16x16x32_bf16 v[8:11], v[140:143], v[222:225], v[8:11]
	v_mfma_f32_16x16x32_bf16 v[52:55], v[144:147], v[172:175], v[52:55]
	v_mfma_f32_16x16x32_bf16 v[48:51], v[152:155], v[172:175], v[48:51]
	v_mfma_f32_16x16x32_bf16 v[36:39], v[144:147], v[202:205], v[36:39]
	v_mfma_f32_16x16x32_bf16 v[32:35], v[152:155], v[202:205], v[32:35]
	v_mfma_f32_16x16x32_bf16 v[20:23], v[144:147], v[210:213], v[20:23]
	v_mfma_f32_16x16x32_bf16 v[16:19], v[152:155], v[210:213], v[16:19]
	v_mfma_f32_16x16x32_bf16 v[4:7], v[144:147], v[218:221], v[4:7]
	v_mfma_f32_16x16x32_bf16 v[0:3], v[152:155], v[218:221], v[0:3]
	v_mfma_f32_16x16x32_bf16 v[52:55], v[148:151], v[198:201], v[52:55]
	v_mfma_f32_16x16x32_bf16 v[48:51], v[168:171], v[198:201], v[48:51]
	v_mfma_f32_16x16x32_bf16 v[36:39], v[148:151], v[206:209], v[36:39]
	v_mfma_f32_16x16x32_bf16 v[32:35], v[168:171], v[206:209], v[32:35]
	v_mfma_f32_16x16x32_bf16 v[20:23], v[148:151], v[214:217], v[20:23]
	v_mfma_f32_16x16x32_bf16 v[16:19], v[168:171], v[214:217], v[16:19]
	v_mfma_f32_16x16x32_bf16 v[4:7], v[148:151], v[222:225], v[4:7]
	v_mfma_f32_16x16x32_bf16 v[0:3], v[168:171], v[222:225], v[0:3]
	s_barrier
	s_add_i32 s54, s54, 2
	s_add_u32 s33, s33, 0x100
	s_addc_u32 s53, s53, 0
	s_cmp_gt_u32 s54, 41
	s_mov_b64 s[44:45], s[46:47]
	s_cbranch_scc0 .LBB0_807
	s_and_b64 vcc, exec, s[18:19]
	s_cbranch_vccz .LBB0_810
	s_barrier
